# v31 plus dense loop SGPR-base tile loads, and post-barrier lgkm waits that only covered the tile-top ds_writes removed
# speedup vs baseline: 1.0206x; 1.0041x over previous
; __device__ __forceinline__ float bflo(unsigned w) { return __uint_as_float(w << 16); }
; __device__ __forceinline__ float bfhi(unsigned w) { return __uint_as_float(w & 0xffff0000u); }
; __device__ __forceinline__ float pairsum(float v) { auto rr = __builtin_amdgcn_permlane32_swap(__float_as_uint(v), __float_as_uint(v), false, false); return __uint_as_float(rr[0]) + __uint_as_float(rr[1]); }
;     constexpr int ND = (MODE == 2) ? 6 : 4, QP = 1536;
;     const int r32 = lane & 31, hi = lane >> 5;
; #pragma unroll
;     for (int qb = 0; qb < 2; ++qb) {
;         __builtin_amdgcn_sched_barrier(0);
;         const bf16_t* src = U.q + (size_t)(32 * qb + r32) * QP + 8 * hi;
;         u32x4 raw[ND];
; #pragma unroll
;         for (int d0 = 0; d0 < ND; ++d0) raw[d0] = *(const u32x4*)(src + 16 * d0);
;         int pos = U.tq0 + 32 * qb + r32; asm volatile("" : "+v"(pos));
;         if constexpr (MODE == 1) {
; #pragma unroll
;             for (int d0 = 0; d0 < ND; ++d0) qf[qb][d0] = __builtin_bit_cast(bf16x8, raw[d0]);
;         } else if constexpr (MODE == 0) {
;             float v[4][8]; float ss = 0.f;
; #pragma unroll
;             for (int d0 = 0; d0 < 4; ++d0)
; #pragma unroll
;                 for (int j = 0; j < 4; ++j) { const unsigned w = raw[d0][j]; v[d0][2 * j] = bflo(w); v[d0][2 * j + 1] = bfhi(w); ss += v[d0][2 * j] * v[d0][2 * j] + v[d0][2 * j + 1] * v[d0][2 * j + 1]; }
;             ss = pairsum(ss);
;             const float rstd = rsqrtf(ss * (1.0f / 64.0f) + EPSN) * C2_64;
; #pragma unroll
;             for (int d0 = 0; d0 < 4; ++d0)
; #pragma unroll
;                 for (int j = 0; j < 8; ++j) v[d0][j] *= rstd * U.gain[16 * d0 + 8 * hi + j];
;             const int row = pos >> 6, col = pos & 63;
; #pragma unroll
;             for (int j = 0; j < 8; ++j) {
;                 __builtin_amdgcn_sched_barrier(0);
;                 const float fi = hi ? invf_c(8 + j) : invf_c(j); float c, s;
;                 rope_cs(row, fi, c, s); { const float x1 = v[0][j], x2 = v[1][j]; v[0][j] = x1 * c - x2 * s; v[1][j] = x2 * c + x1 * s; }
;                 rope_cs(col, fi, c, s); { const float x1 = v[2][j], x2 = v[3][j]; v[2][j] = x1 * c - x2 * s; v[3][j] = x2 * c + x1 * s; }
;             }
.LBB0_436:
	s_add_u32 s46, s12, s46
	s_addc_u32 s47, s13, s47
	s_add_i32 s87, s87, s86
	s_add_u32 s4, s53, s88
	s_addc_u32 s5, s54, s87
	s_lshl_b32 s6, s85, 1
	s_add_u32 s10, s4, s6
	s_addc_u32 s11, s5, 0
	s_lshl_b64 s[6:7], s[44:45], 22
	s_add_u32 s4, s55, s6
	s_addc_u32 s5, s56, s7
	s_lshl_b32 s33, s84, 1
	s_add_u32 s4, s4, s33
	s_load_dwordx2 s[8:9], s[24:25], 0x30
	s_addc_u32 s5, s5, 0
	s_add_u32 s6, s57, s6
	s_addc_u32 s7, s58, s7
	s_lshl_b32 s33, s83, 1
	v_mbcnt_lo_u32_b32 v229, -1, 0
	v_mbcnt_hi_u32_b32 v229, -1, v229
	s_add_u32 s6, s6, s33
	v_lshrrev_b32_e32 v0, 2, v229
	v_and_b32_e32 v228, 63, v229
	v_and_b32_e32 v227, 31, v229
	v_and_b32_e32 v2, 8, v0
	s_addc_u32 s7, s7, 0
	v_cmp_gt_u32_e32 vcc, 32, v228
	v_mul_u32_u24_e32 v0, 0x600, v227
	v_lshlrev_b32_e32 v168, 1, v0
	v_lshl_add_u64 v[0:1], s[10:11], 0, v[168:169]
	v_lshlrev_b32_e32 v168, 1, v2
	v_lshl_add_u64 v[0:1], v[0:1], 0, v[168:169]
	v_or_b32_e32 v32, s82, v227
	global_load_dwordx4 v[20:23], v[0:1], off
	global_load_dwordx4 v[16:19], v[0:1], off offset:32
	global_load_dwordx4 v[28:31], v[0:1], off offset:64
	global_load_dwordx4 v[24:27], v[0:1], off offset:96
	v_cndmask_b32_e64 v93, v206, 1.0, vcc
	v_ashrrev_i32_e32 v33, 6, v32
	v_cvt_f32_i32_e32 v33, v33
	v_and_b32_e32 v32, 63, v32
	v_cvt_f32_ubyte0_e32 v32, v32
	v_cndmask_b32_e32 v95, v207, v208, vcc
	v_mul_f32_e32 v34, v93, v33
	v_mul_f32_e32 v35, 0.15915494, v34
	v_rndne_f32_e32 v35, v35
	v_fmac_f32_e32 v34, 0xc0c90fdb, v35
	v_fmac_f32_e32 v34, 0x343bbd2e, v35
	v_mul_f32_e32 v34, 0.15915494, v34
	v_sin_f32_e32 v74, v34
	v_cos_f32_e32 v76, v34
	v_mul_f32_e32 v34, v93, v32
	v_mul_f32_e32 v35, 0.15915494, v34
	v_rndne_f32_e32 v35, v35
	v_fmac_f32_e32 v34, 0xc0c90fdb, v35
	v_fmac_f32_e32 v34, 0x343bbd2e, v35
	v_mul_f32_e32 v34, 0.15915494, v34
	v_sin_f32_e32 v78, v34
	v_cos_f32_e32 v80, v34
	v_mul_f32_e32 v34, v95, v33
	v_mul_f32_e32 v35, 0.15915494, v34
	v_rndne_f32_e32 v35, v35
	v_fmac_f32_e32 v34, 0xc0c90fdb, v35
	v_fmac_f32_e32 v34, 0x343bbd2e, v35
	v_mul_f32_e32 v34, 0.15915494, v34
	v_sin_f32_e32 v75, v34
	v_cos_f32_e32 v77, v34
	v_mul_f32_e32 v34, v95, v32
	s_movk_i32 s33, 0x7c
	v_mul_f32_e32 v35, 0.15915494, v34
	v_bitop3_b32 v73, v229, s33, v203 bitop3:0xc8
	s_movk_i32 s33, 0xbc
	v_rndne_f32_e32 v35, v35
	v_lshlrev_b32_e32 v61, 2, v2
	v_bitop3_b32 v69, v229, 60, 28 bitop3:0xc8
	v_bitop3_b32 v92, v229, s33, v204 bitop3:0xc8
	s_movk_i32 s33, 0xfc
	v_fmac_f32_e32 v34, 0xc0c90fdb, v35
	s_waitcnt lgkmcnt(0)
	global_load_dwordx3 v[56:58], v61, s[8:9] offset:16
	global_load_dwordx4 v[12:15], v61, s[8:9]
	global_load_dwordx3 v[52:54], v61, s[8:9] offset:80
	global_load_dwordx4 v[8:11], v61, s[8:9] offset:64
	global_load_dwordx3 v[48:50], v61, s[8:9] offset:144
	global_load_dwordx4 v[4:7], v61, s[8:9] offset:128
	global_load_dwordx3 v[44:46], v61, s[8:9] offset:208
	global_load_dwordx4 v[0:3], v61, s[8:9] offset:192
	v_bitop3_b32 v94, v229, s33, v205 bitop3:0xc8
	global_load_dword v83, v69, s[8:9]
	global_load_dword v55, v73, s[8:9]
	global_load_dword v51, v92, s[8:9]
	global_load_dword v47, v94, s[8:9]
	v_fmac_f32_e32 v34, 0x343bbd2e, v35
	v_mul_f32_e32 v34, 0.15915494, v34
	v_cndmask_b32_e32 v105, v209, v210, vcc
	v_sin_f32_e32 v79, v34
	v_cos_f32_e32 v81, v34
	v_mul_f32_e32 v34, v105, v33
	v_mul_f32_e32 v35, 0.15915494, v34
	v_rndne_f32_e32 v35, v35
	v_fmac_f32_e32 v34, 0xc0c90fdb, v35
	v_fmac_f32_e32 v34, 0x343bbd2e, v35
	v_mul_f32_e32 v34, 0.15915494, v34
	v_sin_f32_e32 v84, v34
	v_cos_f32_e32 v86, v34
	v_mul_f32_e32 v34, v105, v32
	v_mul_f32_e32 v35, 0.15915494, v34
	v_rndne_f32_e32 v35, v35
	v_fmac_f32_e32 v34, 0xc0c90fdb, v35
	v_fmac_f32_e32 v34, 0x343bbd2e, v35
	v_mul_f32_e32 v34, 0.15915494, v34
	v_cndmask_b32_e32 v107, v211, v218, vcc
	v_sin_f32_e32 v88, v34
	v_cos_f32_e32 v90, v34
	v_mul_f32_e32 v34, v107, v33
	v_mul_f32_e32 v35, 0.15915494, v34
	v_rndne_f32_e32 v35, v35
	v_fmac_f32_e32 v34, 0xc0c90fdb, v35
	v_fmac_f32_e32 v34, 0x343bbd2e, v35
	v_mul_f32_e32 v34, 0.15915494, v34
	v_sin_f32_e32 v85, v34
	v_cos_f32_e32 v87, v34
	v_mul_f32_e32 v34, v107, v32
	v_mul_f32_e32 v35, 0.15915494, v34
	v_rndne_f32_e32 v35, v35
	v_fmac_f32_e32 v34, 0xc0c90fdb, v35
	v_fmac_f32_e32 v34, 0x343bbd2e, v35
	v_mul_f32_e32 v34, 0.15915494, v34
	s_waitcnt vmcnt(17)
	v_cndmask_b32_e32 v132, v219, v220, vcc
	v_sin_f32_e32 v89, v34
	v_cos_f32_e32 v91, v34
	v_mul_f32_e32 v34, v132, v33
	v_mul_f32_e32 v35, 0.15915494, v34
	v_rndne_f32_e32 v35, v35
	v_fmac_f32_e32 v34, 0xc0c90fdb, v35
	v_fmac_f32_e32 v34, 0x343bbd2e, v35
	v_mul_f32_e32 v34, 0.15915494, v34
	v_sin_f32_e32 v96, v34
	v_cos_f32_e32 v98, v34
	v_mul_f32_e32 v34, v132, v32
	v_mul_f32_e32 v35, 0.15915494, v34
	v_rndne_f32_e32 v35, v35
	v_fmac_f32_e32 v34, 0xc0c90fdb, v35
	v_fmac_f32_e32 v34, 0x343bbd2e, v35
	v_mul_f32_e32 v34, 0.15915494, v34
	v_cndmask_b32_e32 v134, v221, v222, vcc
	v_sin_f32_e32 v100, v34
	v_cos_f32_e32 v102, v34
	v_mul_f32_e32 v34, v134, v33
	v_mul_f32_e32 v35, 0.15915494, v34
	v_rndne_f32_e32 v35, v35
	v_fmac_f32_e32 v34, 0xc0c90fdb, v35
	v_fmac_f32_e32 v34, 0x343bbd2e, v35
	v_mul_f32_e32 v34, 0.15915494, v34
	v_sin_f32_e32 v97, v34
	v_cos_f32_e32 v99, v34
	v_mul_f32_e32 v34, v134, v32
	v_mul_f32_e32 v35, 0.15915494, v34
	v_rndne_f32_e32 v35, v35
	v_fmac_f32_e32 v34, 0xc0c90fdb, v35
	v_fmac_f32_e32 v34, 0x343bbd2e, v35
	v_mul_f32_e32 v34, 0.15915494, v34
	v_cndmask_b32_e32 v104, v223, v224, vcc
	v_sin_f32_e32 v101, v34
	v_cos_f32_e32 v103, v34
	v_mul_f32_e32 v34, v104, v33
	v_mul_f32_e32 v35, 0.15915494, v34
	v_rndne_f32_e32 v35, v35
	v_fmac_f32_e32 v34, 0xc0c90fdb, v35
	v_fmac_f32_e32 v34, 0x343bbd2e, v35
	v_mul_f32_e32 v34, 0.15915494, v34
	v_sin_f32_e32 v108, v34
	v_cos_f32_e32 v110, v34
	v_mul_f32_e32 v34, v104, v32
	v_mul_f32_e32 v35, 0.15915494, v34
	v_rndne_f32_e32 v35, v35
	v_fmac_f32_e32 v34, 0xc0c90fdb, v35
	v_fmac_f32_e32 v34, 0x343bbd2e, v35
	v_cndmask_b32_e32 v178, v225, v226, vcc
	v_mul_f32_e32 v34, 0.15915494, v34
	v_mul_f32_e32 v33, v178, v33
	s_waitcnt vmcnt(17)
; __device__ __forceinline__ float bflo(unsigned w) { return __uint_as_float(w << 16); }
; __device__ __forceinline__ float bfhi(unsigned w) { return __uint_as_float(w & 0xffff0000u); }
; __device__ __forceinline__ float pairsum(float v) { auto rr = __builtin_amdgcn_permlane32_swap(__float_as_uint(v), __float_as_uint(v), false, false); return __uint_as_float(rr[0]) + __uint_as_float(rr[1]); }
;     ...
;         const bf16_t* src = U.q + (size_t)(32 * qb + r32) * QP + 8 * hi;
;         u32x4 raw[ND];
; #pragma unroll
;         for (int d0 = 0; d0 < ND; ++d0) raw[d0] = *(const u32x4*)(src + 16 * d0);
;     ...
;             float v[4][8]; float ss = 0.f;
; #pragma unroll
;             for (int d0 = 0; d0 < 4; ++d0)
; #pragma unroll
;                 for (int j = 0; j < 4; ++j) { const unsigned w = raw[d0][j]; v[d0][2 * j] = bflo(w); v[d0][2 * j + 1] = bfhi(w); ss += v[d0][2 * j] * v[d0][2 * j] + v[d0][2 * j + 1] * v[d0][2 * j + 1]; }
;             ss = pairsum(ss);
;             const float rstd = rsqrtf(ss * (1.0f / 64.0f) + EPSN) * C2_64;
; #pragma unroll
;             for (int d0 = 0; d0 < 4; ++d0)
; #pragma unroll
;                 for (int j = 0; j < 8; ++j) v[d0][j] *= rstd * U.gain[16 * d0 + 8 * hi + j];
	v_sin_f32_e32 v112, v34
	v_cos_f32_e32 v114, v34
	v_mul_f32_e32 v34, 0.15915494, v33
	v_rndne_f32_e32 v34, v34
	v_fmac_f32_e32 v33, 0xc0c90fdb, v34
	v_fmac_f32_e32 v33, 0x343bbd2e, v34
	v_mul_f32_e32 v33, 0.15915494, v33
	v_mul_f32_e32 v32, v178, v32
	v_sin_f32_e32 v109, v33
	v_cos_f32_e32 v111, v33
	v_mul_f32_e32 v33, 0.15915494, v32
	v_rndne_f32_e32 v33, v33
	v_fmac_f32_e32 v32, 0xc0c90fdb, v33
	v_fmac_f32_e32 v32, 0x343bbd2e, v33
	v_mul_f32_e32 v32, 0.15915494, v32
	s_waitcnt vmcnt(13)
	v_and_b32_e32 v119, 0xffff0000, v31
	v_and_b32_e32 v121, 0xffff0000, v30
	v_sin_f32_e32 v113, v32
	v_cos_f32_e32 v115, v32
	v_lshlrev_b32_e32 v118, 16, v31
	v_lshlrev_b32_e32 v120, 16, v30
	v_mov_b32_e32 v32, v119
	v_mov_b32_e32 v33, v121
	s_waitcnt vmcnt(12)
	v_and_b32_e32 v117, 0xffff0000, v27
	v_mov_b32_e32 v30, v118
	v_mov_b32_e32 v31, v120
	v_pk_mul_f32 v[32:33], v[32:33], v[32:33]
	v_and_b32_e32 v123, 0xffff0000, v26
	v_lshlrev_b32_e32 v116, 16, v27
	v_pk_fma_f32 v[30:31], v[30:31], v[30:31], v[32:33]
	v_lshlrev_b32_e32 v122, 16, v26
	v_mov_b32_e32 v32, v117
	v_mov_b32_e32 v33, v123
	v_mov_b32_e32 v26, v116
	v_mov_b32_e32 v27, v122
	v_pk_mul_f32 v[32:33], v[32:33], v[32:33]
	v_and_b32_e32 v127, 0xffff0000, v29
	v_and_b32_e32 v129, 0xffff0000, v28
	v_pk_fma_f32 v[26:27], v[26:27], v[26:27], v[32:33]
	v_lshlrev_b32_e32 v126, 16, v29
	v_lshlrev_b32_e32 v128, 16, v28
	v_mov_b32_e32 v32, v127
	v_mov_b32_e32 v33, v129
	v_and_b32_e32 v125, 0xffff0000, v25
	v_mov_b32_e32 v28, v126
	v_mov_b32_e32 v29, v128
	v_pk_mul_f32 v[32:33], v[32:33], v[32:33]
	v_and_b32_e32 v131, 0xffff0000, v24
	v_and_b32_e32 v173, 0xffff0000, v21
	v_and_b32_e32 v177, 0xffff0000, v20
	v_lshlrev_b32_e32 v124, 16, v25
	v_pk_fma_f32 v[28:29], v[28:29], v[28:29], v[32:33]
	v_lshlrev_b32_e32 v130, 16, v24
	v_mov_b32_e32 v32, v125
	v_mov_b32_e32 v33, v131
	v_and_b32_e32 v165, 0xffff0000, v22
	v_lshlrev_b32_e32 v172, 16, v21
	v_mul_f32_e32 v36, v173, v173
	v_lshlrev_b32_e32 v176, 16, v20
	v_mul_f32_e32 v20, v177, v177
	v_mov_b32_e32 v24, v124
	v_mov_b32_e32 v25, v130
	v_pk_mul_f32 v[32:33], v[32:33], v[32:33]
	v_and_b32_e32 v161, 0xffff0000, v23
	v_and_b32_e32 v159, 0xffff0000, v19
	v_lshlrev_b32_e32 v164, 16, v22
	v_mul_f32_e32 v22, v165, v165
	v_and_b32_e32 v163, 0xffff0000, v18
	v_pk_fma_f32 v[36:37], v[172:173], v[172:173], v[36:37] op_sel_hi:[1,1,0]
	v_and_b32_e32 v167, 0xffff0000, v17
	v_pk_fma_f32 v[20:21], v[176:177], v[176:177], v[20:21] op_sel_hi:[1,1,0]
	v_and_b32_e32 v175, 0xffff0000, v16
	v_pk_fma_f32 v[24:25], v[24:25], v[24:25], v[32:33]
	v_lshlrev_b32_e32 v160, 16, v23
	v_mul_f32_e32 v32, v161, v161
	v_lshlrev_b32_e32 v158, 16, v19
	v_mul_f32_e32 v34, v159, v159
	v_pk_fma_f32 v[22:23], v[164:165], v[164:165], v[22:23] op_sel_hi:[1,1,0]
	v_lshlrev_b32_e32 v162, 16, v18
	v_mul_f32_e32 v18, v163, v163
	v_lshlrev_b32_e32 v166, 16, v17
	v_mul_f32_e32 v38, v167, v167
	v_lshlrev_b32_e32 v174, 16, v16
	v_mul_f32_e32 v16, v175, v175
	v_pk_add_f32 v[20:21], v[20:21], v[36:37]
	v_pk_fma_f32 v[32:33], v[160:161], v[160:161], v[32:33] op_sel_hi:[1,1,0]
	v_pk_fma_f32 v[34:35], v[158:159], v[158:159], v[34:35] op_sel_hi:[1,1,0]
	s_waitcnt vmcnt(11)
	v_mov_b32_e32 v82, v58
	v_pk_fma_f32 v[18:19], v[162:163], v[162:163], v[18:19] op_sel_hi:[1,1,0]
	v_pk_fma_f32 v[38:39], v[166:167], v[166:167], v[38:39] op_sel_hi:[1,1,0]
	v_pk_fma_f32 v[16:17], v[174:175], v[174:175], v[16:17] op_sel_hi:[1,1,0]
	v_pk_add_f32 v[20:21], v[22:23], v[20:21]
	s_nop 0
	v_pk_add_f32 v[20:21], v[32:33], v[20:21]
	s_nop 0
	v_pk_add_f32 v[16:17], v[16:17], v[20:21]
	s_nop 0
	v_pk_add_f32 v[16:17], v[38:39], v[16:17]
	s_nop 0
	v_pk_add_f32 v[16:17], v[18:19], v[16:17]
	s_nop 0
	v_pk_add_f32 v[16:17], v[34:35], v[16:17]
	s_nop 0
	v_pk_add_f32 v[16:17], v[28:29], v[16:17] op_sel:[1,0] op_sel_hi:[0,1]
	v_pk_add_f32 v[16:17], v[28:29], v[16:17]
	s_nop 0
	v_pk_add_f32 v[16:17], v[30:31], v[16:17] op_sel:[1,0] op_sel_hi:[0,1]
	v_pk_add_f32 v[16:17], v[30:31], v[16:17]
	s_nop 0
	v_pk_add_f32 v[16:17], v[24:25], v[16:17] op_sel:[1,0] op_sel_hi:[0,1]
	v_pk_add_f32 v[16:17], v[24:25], v[16:17]
	s_nop 0
	v_pk_add_f32 v[16:17], v[26:27], v[16:17] op_sel:[1,0] op_sel_hi:[0,1]
	v_pk_add_f32 v[192:193], v[26:27], v[16:17]
	s_nop 0
	v_mov_b32_e32 v65, v192
	s_nop 1
	v_permlane32_swap_b32_e32 v192, v65
	v_or_b32_e32 v18, 32, v228
	v_mul_u32_u24_e32 v16, 0x600, v18
	v_lshlrev_b32_e32 v16, 1, v16
	v_mov_b32_e32 v17, v169
	v_lshl_add_u64 v[16:17], s[10:11], 0, v[16:17]
	v_lshl_add_u64 v[16:17], v[16:17], 0, v[168:169]
	global_load_dwordx4 v[36:39], v[16:17], off
	global_load_dwordx4 v[32:35], v[16:17], off offset:32
	global_load_dwordx4 v[194:197], v[16:17], off offset:64
	global_load_dwordx4 v[40:43], v[16:17], off offset:96
	v_or_b32_e32 v106, s82, v18
	global_load_dwordx3 v[58:60], v61, s[8:9] offset:16
	global_load_dwordx4 v[16:19], v61, s[8:9]
	global_load_dwordx3 v[62:64], v61, s[8:9] offset:80
	global_load_dwordx4 v[20:23], v61, s[8:9] offset:64
	global_load_dwordx3 v[66:68], v61, s[8:9] offset:144
	global_load_dwordx4 v[24:27], v61, s[8:9] offset:128
	global_load_dwordx3 v[70:72], v61, s[8:9] offset:208
	global_load_dwordx4 v[28:31], v61, s[8:9] offset:192
	s_nop 0
	global_load_dword v69, v69, s[8:9]
	s_nop 0
	global_load_dword v61, v73, s[8:9]
	global_load_dword v133, v92, s[8:9]
	s_nop 0
	global_load_dword v73, v94, s[8:9]
	v_and_b32_e32 v92, 63, v106
	v_cvt_f32_ubyte0_e32 v168, v92
	v_mul_f32_e32 v92, v104, v168
	v_mul_f32_e32 v94, 0.15915494, v92
	v_rndne_f32_e32 v94, v94
	v_fmac_f32_e32 v92, 0xc0c90fdb, v94
	v_fmac_f32_e32 v92, 0x343bbd2e, v94
	v_ashrrev_i32_e32 v94, 6, v106
	v_mul_f32_e32 v135, v134, v168
;     ...
;             for (int j = 0; j < 8; ++j) {
;                 __builtin_amdgcn_sched_barrier(0);
;                 const float fi = hi ? invf_c(8 + j) : invf_c(j); float c, s;
;                 rope_cs(row, fi, c, s); { const float x1 = v[0][j], x2 = v[1][j]; v[0][j] = x1 * c - x2 * s; v[1][j] = x2 * c + x1 * s; }
;                 rope_cs(col, fi, c, s); { const float x1 = v[2][j], x2 = v[3][j]; v[2][j] = x1 * c - x2 * s; v[3][j] = x2 * c + x1 * s; }
;             }
	v_cvt_f32_i32_e32 v179, v94
	v_mul_f32_e32 v136, 0.15915494, v135
	v_rndne_f32_e32 v136, v136
	v_fmac_f32_e32 v135, 0xc0c90fdb, v136
	v_fmac_f32_e32 v135, 0x343bbd2e, v136
	v_mul_f32_e32 v136, 0.15915494, v135
	v_mul_f32_e32 v134, v134, v179
	v_cos_f32_e32 v135, v136
	v_sin_f32_e32 v137, v136
	v_mul_f32_e32 v136, 0.15915494, v134
	v_rndne_f32_e32 v136, v136
	v_fmac_f32_e32 v134, 0xc0c90fdb, v136
	v_fmac_f32_e32 v134, 0x343bbd2e, v136
	v_mul_f32_e32 v134, 0.15915494, v134
	v_cos_f32_e32 v139, v134
	v_sin_f32_e32 v141, v134
	v_mul_f32_e32 v134, v132, v168
	v_mul_f32_e32 v132, v132, v179
	v_mul_f32_e32 v138, 0.15915494, v132
	v_rndne_f32_e32 v138, v138
	v_fmac_f32_e32 v132, 0xc0c90fdb, v138
	v_fmac_f32_e32 v132, 0x343bbd2e, v138
	v_mul_f32_e32 v132, 0.15915494, v132
	v_cos_f32_e32 v138, v132
	v_sin_f32_e32 v140, v132
	v_mul_f32_e32 v132, v107, v168
	v_mul_f32_e32 v142, 0.15915494, v132
	v_rndne_f32_e32 v142, v142
	v_fmac_f32_e32 v132, 0xc0c90fdb, v142
	v_fmac_f32_e32 v132, 0x343bbd2e, v142
	v_mul_f32_e32 v132, 0.15915494, v132
	v_mul_f32_e32 v107, v107, v179
	v_cos_f32_e32 v143, v132
	v_sin_f32_e32 v145, v132
	v_mul_f32_e32 v132, 0.15915494, v107
	v_rndne_f32_e32 v132, v132
	v_fmac_f32_e32 v107, 0xc0c90fdb, v132
	v_fmac_f32_e32 v107, 0x343bbd2e, v132
	v_mul_f32_e32 v107, 0.15915494, v107
	v_cos_f32_e32 v147, v107
	v_sin_f32_e32 v151, v107
	v_mul_f32_e32 v107, v105, v168
	v_mul_f32_e32 v132, 0.15915494, v107
	v_rndne_f32_e32 v132, v132
	v_fmac_f32_e32 v107, 0xc0c90fdb, v132
	v_fmac_f32_e32 v107, 0x343bbd2e, v132
	v_mul_f32_e32 v107, 0.15915494, v107
	v_mul_f32_e32 v105, v105, v179
	v_cos_f32_e32 v142, v107
	v_sin_f32_e32 v144, v107
	v_mul_f32_e32 v107, 0.15915494, v105
	v_rndne_f32_e32 v107, v107
	v_fmac_f32_e32 v105, 0xc0c90fdb, v107
	v_fmac_f32_e32 v105, 0x343bbd2e, v107
	v_mul_f32_e32 v105, 0.15915494, v105
	v_cos_f32_e32 v146, v105
	v_sin_f32_e32 v150, v105
	v_mul_f32_e32 v105, v95, v168
	v_mul_f32_e32 v107, 0.15915494, v105
	v_rndne_f32_e32 v107, v107
	v_fmac_f32_e32 v105, 0xc0c90fdb, v107
	v_fmac_f32_e32 v105, 0x343bbd2e, v107
	v_mul_f32_e32 v105, 0.15915494, v105
	v_mul_f32_e32 v95, v95, v179
	v_cos_f32_e32 v153, v105
	v_sin_f32_e32 v155, v105
	v_mul_f32_e32 v105, 0.15915494, v95
	v_rndne_f32_e32 v105, v105
	v_fmac_f32_e32 v95, 0xc0c90fdb, v105
	v_fmac_f32_e32 v95, 0x343bbd2e, v105
	v_mul_f32_e32 v95, 0.15915494, v95
	v_cos_f32_e32 v149, v95
	v_sin_f32_e32 v157, v95
	v_mul_f32_e32 v95, v93, v168
	v_mul_f32_e32 v105, 0.15915494, v95
	v_rndne_f32_e32 v105, v105
	v_fmac_f32_e32 v95, 0xc0c90fdb, v105
	v_fmac_f32_e32 v95, 0x343bbd2e, v105
	v_mul_f32_e32 v95, 0.15915494, v95
	v_mul_f32_e32 v93, v93, v179
	v_cos_f32_e32 v152, v95
	v_sin_f32_e32 v154, v95
	v_mul_f32_e32 v95, 0.15915494, v93
	v_rndne_f32_e32 v95, v95
	v_fmac_f32_e32 v93, 0xc0c90fdb, v95
	v_fmac_f32_e32 v93, 0x343bbd2e, v95
	v_mul_f32_e32 v93, 0.15915494, v93
	v_cos_f32_e32 v148, v93
	v_sin_f32_e32 v156, v93
	v_mul_f32_e32 v93, v178, v179
	v_mul_f32_e32 v95, 0.15915494, v93
	v_rndne_f32_e32 v95, v95
	v_fmac_f32_e32 v93, 0xc0c90fdb, v95
	v_fmac_f32_e32 v93, 0x343bbd2e, v95
	v_mul_f32_e32 v104, v104, v179
	v_mul_f32_e32 v93, 0.15915494, v93
	s_waitcnt vmcnt(13)
	v_and_b32_e32 v179, 0xffff0000, v197
	v_and_b32_e32 v183, 0xffff0000, v196
	v_sin_f32_e32 v105, v93
	v_cos_f32_e32 v107, v93
	v_mul_f32_e32 v93, v178, v168
	v_lshlrev_b32_e32 v178, 16, v197
	v_lshlrev_b32_e32 v182, 16, v196
	v_mov_b32_e32 v186, v179
	v_mov_b32_e32 v187, v183
	v_mov_b32_e32 v184, v178
	v_mov_b32_e32 v185, v182
	v_pk_mul_f32 v[186:187], v[186:187], v[186:187]
	s_waitcnt vmcnt(12)
	v_and_b32_e32 v181, 0xffff0000, v43
	v_pk_fma_f32 v[230:231], v[184:185], v[184:185], v[186:187]
	v_and_b32_e32 v187, 0xffff0000, v42
	v_lshlrev_b32_e32 v180, 16, v43
	v_lshlrev_b32_e32 v186, 16, v42
	v_mov_b32_e32 v184, v181
	v_mov_b32_e32 v185, v187
	v_mov_b32_e32 v42, v180
	v_mov_b32_e32 v43, v186
	v_pk_mul_f32 v[184:185], v[184:185], v[184:185]
	v_and_b32_e32 v189, 0xffff0000, v41
	v_pk_fma_f32 v[232:233], v[42:43], v[42:43], v[184:185]
	v_and_b32_e32 v185, 0xffff0000, v195
	v_and_b32_e32 v43, 0xffff0000, v194
	v_lshlrev_b32_e32 v184, 16, v195
	v_lshlrev_b32_e32 v42, 16, v194
	v_mov_b32_e32 v194, v185
	v_mov_b32_e32 v195, v43
	v_mov_b32_e32 v190, v184
	v_mov_b32_e32 v191, v42
	v_pk_mul_f32 v[194:195], v[194:195], v[194:195]
	v_lshlrev_b32_e32 v188, 16, v41
	v_pk_fma_f32 v[234:235], v[190:191], v[190:191], v[194:195]
	v_and_b32_e32 v191, 0xffff0000, v40
	v_lshlrev_b32_e32 v190, 16, v40
	v_mov_b32_e32 v194, v189
	v_mov_b32_e32 v195, v191
	v_and_b32_e32 v199, 0xffff0000, v34
	v_mul_f32_e32 v106, 0.15915494, v104
	v_mul_f32_e32 v136, 0.15915494, v134
	v_mov_b32_e32 v40, v188
	v_mov_b32_e32 v41, v190
	v_pk_mul_f32 v[194:195], v[194:195], v[194:195]
	v_and_b32_e32 v197, 0xffff0000, v38
	v_lshlrev_b32_e32 v198, 16, v34
	v_mul_f32_e32 v34, v199, v199
	v_rndne_f32_e32 v106, v106
	v_rndne_f32_e32 v136, v136
	v_pk_fma_f32 v[236:237], v[40:41], v[40:41], v[194:195]
	v_lshlrev_b32_e32 v194, 16, v35
	v_and_b32_e32 v195, 0xffff0000, v35
	v_lshlrev_b32_e32 v196, 16, v38
	v_mul_f32_e32 v38, v197, v197
	v_pk_fma_f32 v[244:245], v[198:199], v[198:199], v[34:35] op_sel_hi:[1,1,0]
	v_and_b32_e32 v35, 0xffff0000, v37
	v_fmac_f32_e32 v104, 0xc0c90fdb, v106
	v_fmac_f32_e32 v134, 0xc0c90fdb, v136
	v_pk_fma_f32 v[242:243], v[196:197], v[196:197], v[38:39] op_sel_hi:[1,1,0]
	v_lshlrev_b32_e32 v34, 16, v37
	v_mul_f32_e32 v38, v35, v35
	v_and_b32_e32 v201, 0xffff0000, v33
	v_fmac_f32_e32 v104, 0x343bbd2e, v106
	v_fmac_f32_e32 v134, 0x343bbd2e, v136
	v_pk_fma_f32 v[246:247], v[34:35], v[34:35], v[38:39] op_sel_hi:[1,1,0]
	v_lshlrev_b32_e32 v200, 16, v33
	v_mul_f32_e32 v38, v201, v201
	v_mul_f32_e32 v104, 0.15915494, v104
	v_mul_f32_e32 v136, 0.15915494, v134
	v_mul_f32_e32 v95, 0.15915494, v93
	v_lshlrev_b32_e32 v40, 16, v39
	v_and_b32_e32 v41, 0xffff0000, v39
	v_pk_fma_f32 v[248:249], v[200:201], v[200:201], v[38:39] op_sel_hi:[1,1,0]
	v_and_b32_e32 v39, 0xffff0000, v36
	v_cos_f32_e32 v106, v104
	v_sin_f32_e32 v104, v104
	v_cos_f32_e32 v134, v136
	v_sin_f32_e32 v136, v136
	v_rndne_f32_e32 v95, v95
	v_lshlrev_b32_e32 v38, 16, v36
	v_mul_f32_e32 v36, v39, v39
	v_fmac_f32_e32 v93, 0xc0c90fdb, v95
	s_waitcnt vmcnt(7)
; __device__ __forceinline__ unsigned pk(float lo, float hi) { f32x2_t v = {lo, hi}; bf16x2_t b = __builtin_convertvector(v, bf16x2_t); return __builtin_bit_cast(unsigned, b); }
; __device__ __forceinline__ float pairsum(float v) { auto rr = __builtin_amdgcn_permlane32_swap(__float_as_uint(v), __float_as_uint(v), false, false); return __uint_as_float(rr[0]) + __uint_as_float(rr[1]); }
;     ...
;             ss = pairsum(ss);
;             const float rstd = rsqrtf(ss * (1.0f / 64.0f) + EPSN) * C2_64;
; #pragma unroll
;             for (int d0 = 0; d0 < 4; ++d0)
; #pragma unroll
;                 for (int j = 0; j < 8; ++j) v[d0][j] *= rstd * U.gain[16 * d0 + 8 * hi + j];
;             const int row = pos >> 6, col = pos & 63;
; #pragma unroll
;             for (int j = 0; j < 8; ++j) {
;                 __builtin_amdgcn_sched_barrier(0);
;                 const float fi = hi ? invf_c(8 + j) : invf_c(j); float c, s;
;                 rope_cs(row, fi, c, s); { const float x1 = v[0][j], x2 = v[1][j]; v[0][j] = x1 * c - x2 * s; v[1][j] = x2 * c + x1 * s; }
;                 rope_cs(col, fi, c, s); { const float x1 = v[2][j], x2 = v[3][j]; v[2][j] = x1 * c - x2 * s; v[3][j] = x2 * c + x1 * s; }
;             }
; #pragma unroll
;             for (int d0 = 0; d0 < 4; ++d0) { u32x4 w; w.x = pk(v[d0][0], v[d0][1]); w.y = pk(v[d0][2], v[d0][3]); w.z = pk(v[d0][4], v[d0][5]); w.w = pk(v[d0][6], v[d0][7]); qf[qb][d0] = __builtin_bit_cast(bf16x8, w); }
	v_mov_b32_e32 v132, v68
	v_mul_f32_e32 v68, v41, v41
	v_pk_fma_f32 v[250:251], v[38:39], v[38:39], v[36:37] op_sel_hi:[1,1,0]
	v_and_b32_e32 v37, 0xffff0000, v32
	v_fmac_f32_e32 v93, 0x343bbd2e, v95
	s_waitcnt vmcnt(3)
	v_pk_fma_f32 v[238:239], v[40:41], v[40:41], v[68:69] op_sel_hi:[1,1,0]
	v_mul_f32_e32 v68, v195, v195
	v_lshlrev_b32_e32 v36, 16, v32
	v_mul_f32_e32 v32, v37, v37
	v_mul_f32_e32 v92, 0.15915494, v92
	v_mul_f32_e32 v95, 0.15915494, v93
	v_pk_fma_f32 v[240:241], v[194:195], v[194:195], v[68:69] op_sel_hi:[1,1,0]
	v_mov_b32_e32 v68, v60
	v_mov_b32_e32 v60, v64
	v_pk_fma_f32 v[32:33], v[36:37], v[36:37], v[32:33] op_sel_hi:[1,1,0]
	v_pk_add_f32 v[246:247], v[250:251], v[246:247]
	v_cos_f32_e32 v94, v92
	v_sin_f32_e32 v92, v92
	v_sin_f32_e32 v93, v95
	v_cos_f32_e32 v95, v95
	v_pk_add_f32 v[242:243], v[242:243], v[246:247]
	s_nop 0
	v_pk_add_f32 v[238:239], v[238:239], v[242:243]
	s_mov_b32 s8, 0x3c800000
	v_pk_add_f32 v[32:33], v[32:33], v[238:239]
	s_mov_b32 s33, 0
	v_pk_add_f32 v[32:33], v[248:249], v[32:33]
	s_nop 0
	v_pk_add_f32 v[32:33], v[244:245], v[32:33]
	s_nop 0
	v_pk_add_f32 v[32:33], v[240:241], v[32:33]
	s_nop 0
	v_pk_add_f32 v[32:33], v[234:235], v[32:33] op_sel:[1,0] op_sel_hi:[0,1]
	v_pk_add_f32 v[32:33], v[234:235], v[32:33]
	s_nop 0
	v_pk_add_f32 v[32:33], v[230:231], v[32:33] op_sel:[1,0] op_sel_hi:[0,1]
	v_pk_add_f32 v[32:33], v[230:231], v[32:33]
	s_nop 0
	v_pk_add_f32 v[32:33], v[236:237], v[32:33] op_sel:[1,0] op_sel_hi:[0,1]
	v_pk_add_f32 v[32:33], v[236:237], v[32:33]
	s_nop 0
	v_pk_add_f32 v[32:33], v[232:233], v[32:33] op_sel:[1,0] op_sel_hi:[0,1]
	v_pk_add_f32 v[32:33], v[232:233], v[32:33]
	s_nop 0
	v_mov_b32_e32 v64, v32
	s_nop 1
	v_permlane32_swap_b32_e32 v32, v64
	v_mov_b32_e32 v33, v192
	v_pk_add_f32 v[32:33], v[32:33], v[64:65]
	s_nop 0
	v_pk_fma_f32 v[32:33], v[32:33], s[8:9], v[170:171] op_sel_hi:[1,0,0]
	s_nop 0
	v_mul_f32_e32 v64, 0x4b800000, v33
	v_cmp_gt_f32_e32 vcc, s71, v33
	s_nop 1
	v_cndmask_b32_e32 v33, v33, v64, vcc
	v_rsq_f32_e32 v33, v33
	s_nop 0
	v_mul_f32_e32 v64, 0x45800000, v33
	v_cndmask_b32_e32 v33, v33, v64, vcc
	v_mul_f32_e32 v64, 0x3e38aa3b, v33
	v_pk_mul_f32 v[8:9], v[8:9], v[64:65] op_sel_hi:[1,0]
	v_pk_mul_f32 v[12:13], v[12:13], v[64:65] op_sel_hi:[1,0]
	v_pk_mul_f32 v[8:9], v[8:9], v[174:175]
	v_pk_mul_f32 v[12:13], v[12:13], v[176:177]
	v_pk_mul_f32 v[14:15], v[14:15], v[64:65] op_sel_hi:[1,0]
	v_pk_mul_f32 v[56:57], v[56:57], v[64:65] op_sel_hi:[1,0]
	v_pk_mul_f32 v[82:83], v[82:83], v[64:65] op_sel_hi:[1,0]
	v_pk_mul_f32 v[10:11], v[64:65], v[10:11] op_sel_hi:[0,1]
	v_pk_mul_f32 v[52:53], v[64:65], v[52:53] op_sel_hi:[0,1]
	v_pk_mul_f32 v[54:55], v[64:65], v[54:55] op_sel_hi:[0,1]
	v_pk_mul_f32 v[4:5], v[64:65], v[4:5] op_sel_hi:[0,1]
	v_pk_mul_f32 v[6:7], v[64:65], v[6:7] op_sel_hi:[0,1]
	v_pk_mul_f32 v[48:49], v[64:65], v[48:49] op_sel_hi:[0,1]
	v_pk_mul_f32 v[50:51], v[64:65], v[50:51] op_sel_hi:[0,1]
	v_pk_mul_f32 v[0:1], v[64:65], v[0:1] op_sel_hi:[0,1]
	v_pk_mul_f32 v[2:3], v[64:65], v[2:3] op_sel_hi:[0,1]
	v_pk_mul_f32 v[44:45], v[64:65], v[44:45] op_sel_hi:[0,1]
	v_pk_mul_f32 v[46:47], v[64:65], v[46:47] op_sel_hi:[0,1]
	v_pk_mul_f32 v[64:65], v[74:75], v[8:9]
	v_pk_mul_f32 v[0:1], v[0:1], v[130:131]
	v_pk_fma_f32 v[64:65], v[76:77], v[12:13], v[64:65] neg_lo:[0,0,1] neg_hi:[0,0,1]
	v_pk_mul_f32 v[12:13], v[74:75], v[12:13]
	v_pk_mul_f32 v[10:11], v[10:11], v[166:167]
	v_pk_mul_f32 v[4:5], v[4:5], v[128:129]
	v_pk_fma_f32 v[8:9], v[76:77], v[8:9], v[12:13]
	v_pk_mul_f32 v[12:13], v[78:79], v[0:1]
	v_pk_mul_f32 v[0:1], v[80:81], v[0:1]
	v_pk_mul_f32 v[14:15], v[14:15], v[172:173]
	v_pk_mul_f32 v[2:3], v[2:3], v[124:125]
	v_pk_fma_f32 v[74:75], v[80:81], v[4:5], v[12:13] neg_lo:[0,0,1] neg_hi:[0,0,1]
	v_pk_fma_f32 v[76:77], v[78:79], v[4:5], v[0:1]
	v_pk_mul_f32 v[4:5], v[86:87], v[10:11]
	v_pk_mul_f32 v[52:53], v[52:53], v[162:163]
	v_pk_mul_f32 v[6:7], v[6:7], v[126:127]
	v_pk_mul_f32 v[0:1], v[84:85], v[10:11]
	v_pk_fma_f32 v[78:79], v[84:85], v[14:15], v[4:5]
	v_pk_mul_f32 v[4:5], v[88:89], v[2:3]
	v_pk_mul_f32 v[56:57], v[56:57], v[164:165]
	v_pk_mul_f32 v[44:45], v[44:45], v[122:123]
	v_pk_fma_f32 v[0:1], v[86:87], v[14:15], v[0:1] neg_lo:[0,0,1] neg_hi:[0,0,1]
	v_pk_fma_f32 v[80:81], v[90:91], v[6:7], v[4:5] neg_lo:[0,0,1] neg_hi:[0,0,1]
	v_pk_mul_f32 v[2:3], v[90:91], v[2:3]
	v_pk_mul_f32 v[4:5], v[98:99], v[52:53]
	v_pk_mul_f32 v[54:55], v[54:55], v[158:159]
	v_pk_mul_f32 v[48:49], v[48:49], v[120:121]
	v_pk_mul_f32 v[46:47], v[46:47], v[116:117]
	v_pk_fma_f32 v[84:85], v[88:89], v[6:7], v[2:3]
	v_pk_mul_f32 v[2:3], v[96:97], v[52:53]
	v_pk_fma_f32 v[52:53], v[96:97], v[56:57], v[4:5]
	v_pk_mul_f32 v[4:5], v[100:101], v[44:45]
	v_cvt_pk_bf16_f32 v117, v0, v1
	v_add_u32_e32 v0, s36, v229
	v_lshlrev_b32_e32 v1, 4, v229
	v_pk_mul_f32 v[82:83], v[82:83], v[160:161]
	v_pk_fma_f32 v[2:3], v[98:99], v[56:57], v[2:3] neg_lo:[0,0,1] neg_hi:[0,0,1]
	v_pk_fma_f32 v[56:57], v[102:103], v[48:49], v[4:5] neg_lo:[0,0,1] neg_hi:[0,0,1]
	v_pk_mul_f32 v[4:5], v[102:103], v[44:45]
	v_pk_mul_f32 v[6:7], v[110:111], v[54:55]
	v_ashrrev_i32_e32 v33, 3, v0
	v_and_b32_e32 v86, 0x70, v1
	v_pk_mul_f32 v[50:51], v[50:51], v[118:119]
	v_pk_fma_f32 v[44:45], v[100:101], v[48:49], v[4:5]
	v_pk_fma_f32 v[48:49], v[108:109], v[82:83], v[6:7]
	v_pk_mul_f32 v[6:7], v[112:113], v[46:47]
	v_lshl_or_b32 v168, v33, 8, v86
	v_pk_mul_f32 v[4:5], v[108:109], v[54:55]
	v_pk_fma_f32 v[54:55], v[114:115], v[50:51], v[6:7] neg_lo:[0,0,1] neg_hi:[0,0,1]
	v_pk_mul_f32 v[6:7], v[114:115], v[46:47]
	v_cvt_pk_bf16_f32 v116, v64, v65
	v_lshl_add_u64 v[64:65], s[4:5], 0, v[168:169]
; #define BAR_LDS() asm volatile("s_waitcnt lgkmcnt(0)\n\ts_barrier" ::: "memory")
; #define ATT_LOADS(RK, RR, RV, tt) do { RK = *(const u32x4*)((const char*)(U.k + (size_t)(tt) * 64 * KP) + kgo); if (MODE == 2) RR = *(const u32x2*)((const char*)(U.kr + (size_t)(tt) * 64 * 32) + krgo); \
;         RV = *(const u32x4*)((const char*)(U.vt + (size_t)(tt) * VTS) + vgo); } while (0)
; #define ATT_LOAD(tt) ATT_LOADS(rk, rr, rv, tt)
; #define ATT_STORE(ss) ATT_STORES(rk, rr, rv, ss)
; template <int MODE, bool FAST> __device__ __forceinline__ bool attn_unit(LAS unsigned char* lds, const AttU& U, const int wv) {
;     ...
;     const int NT = U.kt1 - U.kt0;
;     ATT_LOAD(U.kt0); ATT_STORE(0);
;     if (NT > 1) { ATT_LOAD(U.kt0 + 1); ATT_STORE(1); }
;     if (NT > 2) ATT_LOAD(U.kt0 + 2);
;     if constexpr (FAST) { if (NT > 3) ATT_LOADS(rk2, rr2, rv2, U.kt0 + 3); }
;     BAR_LDS();
	v_pk_fma_f32 v[46:47], v[112:113], v[50:51], v[6:7]
	v_cvt_pk_bf16_f32 v120, v8, v9
	v_lshlrev_b32_e32 v50, 4, v0
	v_mov_b32_e32 v51, v169
	v_add_co_u32_e32 v8, vcc, s72, v64
	v_pk_fma_f32 v[4:5], v[110:111], v[82:83], v[4:5] neg_lo:[0,0,1] neg_hi:[0,0,1]
	v_lshl_add_u64 v[82:83], s[6:7], 0, v[50:51]
	v_addc_co_u32_e32 v9, vcc, 0, v65, vcc
	v_add_co_u32_e32 v12, vcc, s72, v82
	v_cvt_pk_bf16_f32 v118, v2, v3
	s_nop 0
	v_addc_co_u32_e32 v13, vcc, 0, v83, vcc
	v_cvt_pk_bf16_f32 v119, v4, v5
	global_load_dwordx4 v[0:3], v168, s[4:5]
	global_load_dwordx4 v[4:7], v50, s[6:7]
	s_nop 0
	global_load_dwordx4 v[8:11], v[8:9], off
	s_nop 0
	global_load_dwordx4 v[12:15], v[12:13], off
	v_cvt_pk_bf16_f32 v123, v48, v49
	v_mul_f32_e32 v48, 0x4b800000, v32
	v_cmp_gt_f32_e32 vcc, s71, v32
	v_cvt_pk_bf16_f32 v130, v44, v45
	v_cvt_pk_bf16_f32 v122, v52, v53
	v_cndmask_b32_e32 v32, v32, v48, vcc
	v_rsq_f32_e32 v32, v32
	v_cvt_pk_bf16_f32 v126, v56, v57
	v_cvt_pk_bf16_f32 v127, v54, v55
	v_cvt_pk_bf16_f32 v131, v46, v47
	v_mul_f32_e32 v44, 0x45800000, v32
	v_cndmask_b32_e32 v32, v32, v44, vcc
	v_mul_f32_e32 v32, 0x3e38aa3b, v32
	v_pk_mul_f32 v[30:31], v[32:33], v[30:31] op_sel_hi:[0,1]
	v_pk_mul_f32 v[26:27], v[32:33], v[26:27] op_sel_hi:[0,1]
	v_pk_mul_f32 v[30:31], v[30:31], v[188:189]
	v_pk_mul_f32 v[18:19], v[18:19], v[32:33] op_sel_hi:[1,0]
	v_pk_mul_f32 v[22:23], v[32:33], v[22:23] op_sel_hi:[0,1]
	v_pk_mul_f32 v[26:27], v[26:27], v[184:185]
	v_pk_mul_f32 v[18:19], v[18:19], v[34:35]
	v_pk_mul_f32 v[22:23], v[22:23], v[200:201]
	v_pk_mul_f32 v[34:35], v[142:143], v[30:31]
	v_pk_mul_f32 v[30:31], v[144:145], v[30:31]
	v_pk_mul_f32 v[48:49], v[68:69], v[32:33] op_sel_hi:[1,0]
	v_pk_fma_f32 v[34:35], v[144:145], v[26:27], v[34:35]
	v_pk_fma_f32 v[26:27], v[142:143], v[26:27], v[30:31] neg_lo:[0,0,1] neg_hi:[0,0,1]
	v_pk_mul_f32 v[30:31], v[146:147], v[22:23]
	v_pk_mul_f32 v[22:23], v[150:151], v[22:23]
	s_waitcnt vmcnt(5)
	v_pk_mul_f32 v[44:45], v[32:33], v[132:133] op_sel_hi:[0,1]
	s_waitcnt vmcnt(4)
	v_pk_mul_f32 v[46:47], v[32:33], v[72:73] op_sel_hi:[0,1]
	v_pk_mul_f32 v[40:41], v[48:49], v[40:41]
	v_pk_mul_f32 v[48:49], v[32:33], v[60:61] op_sel_hi:[0,1]
	v_pk_mul_f32 v[52:53], v[32:33], v[66:67] op_sel_hi:[0,1]
	v_pk_mul_f32 v[54:55], v[32:33], v[70:71] op_sel_hi:[0,1]
	v_pk_mul_f32 v[56:57], v[58:59], v[32:33] op_sel_hi:[1,0]
	v_pk_mul_f32 v[58:59], v[32:33], v[62:63] op_sel_hi:[0,1]
	v_pk_fma_f32 v[30:31], v[150:151], v[18:19], v[30:31]
	v_pk_fma_f32 v[18:19], v[146:147], v[18:19], v[22:23] neg_lo:[0,0,1] neg_hi:[0,0,1]
	v_pk_mul_f32 v[22:23], v[32:33], v[24:25] op_sel_hi:[0,1]
	v_pk_mul_f32 v[24:25], v[32:33], v[28:29] op_sel_hi:[0,1]
	v_pk_mul_f32 v[16:17], v[16:17], v[32:33] op_sel_hi:[1,0]
	v_pk_mul_f32 v[20:21], v[20:21], v[32:33] op_sel_hi:[1,0]
	v_mul_lo_u32 v33, v33, s60
	v_add3_u32 v173, v33, v86, 0
	s_waitcnt vmcnt(3)
	ds_write_b128 v173, v[0:3]
	s_waitcnt vmcnt(2)
	ds_write_b128 v173, v[4:7] offset:9216
	s_waitcnt vmcnt(1)
	ds_write_b128 v173, v[8:11] offset:18432
	s_waitcnt vmcnt(0)
	ds_write_b128 v173, v[12:15] offset:27648
	v_add_co_u32_e32 v0, vcc, s73, v64
	v_pk_mul_f32 v[54:55], v[54:55], v[186:187]
	s_nop 0
	v_addc_co_u32_e32 v1, vcc, 0, v65, vcc
	v_pk_mul_f32 v[52:53], v[52:53], v[182:183]
	v_pk_mul_f32 v[58:59], v[58:59], v[198:199]
	v_pk_mul_f32 v[60:61], v[134:135], v[54:55]
	v_pk_mul_f32 v[54:55], v[136:137], v[54:55]
	v_add_co_u32_e32 v2, vcc, s73, v82
	v_pk_mul_f32 v[56:57], v[56:57], v[196:197]
	v_pk_fma_f32 v[60:61], v[136:137], v[52:53], v[60:61]
	v_pk_fma_f32 v[52:53], v[134:135], v[52:53], v[54:55] neg_lo:[0,0,1] neg_hi:[0,0,1]
	v_pk_mul_f32 v[54:55], v[138:139], v[58:59]
	v_pk_mul_f32 v[58:59], v[140:141], v[58:59]
	v_addc_co_u32_e32 v3, vcc, 0, v83, vcc
	v_pk_fma_f32 v[54:55], v[140:141], v[56:57], v[54:55]
	v_pk_fma_f32 v[56:57], v[138:139], v[56:57], v[58:59] neg_lo:[0,0,1] neg_hi:[0,0,1]
	global_load_dwordx4 v[132:135], v[0:1], off
	global_load_dwordx4 v[136:139], v[2:3], off
	v_add_co_u32_e32 v0, vcc, s74, v64
	v_bfe_u32 v32, v229, 5, 1
	s_nop 0
	v_addc_co_u32_e32 v1, vcc, 0, v65, vcc
	v_add_co_u32_e32 v2, vcc, s74, v82
	v_lshlrev_b32_e32 v172, 4, v32
	s_nop 0
	v_addc_co_u32_e32 v3, vcc, 0, v83, vcc
	global_load_dwordx4 v[140:143], v[0:1], off
	global_load_dwordx4 v[144:147], v[2:3], off
	v_mul_u32_u24_e32 v0, 0x90, v227
	s_waitcnt lgkmcnt(0)
	s_barrier
; #define LAS __attribute__((address_space(3)))
; template <int MODE, bool FAST> __device__ __forceinline__ bool attn_unit(LAS unsigned char* lds, const AttU& U, const int wv) {
;     ...
;     pb[1][0] = (bf16x8){0, 0, 0, 0, 0, 0, 0, 0}; pb[1][1] = pb[1][0];
;     ATT_QK(0, 0, 0);
;     bf16x8 kpre[NPRE > 0 ? NPRE : 1];
; #pragma unroll
;     for (int i_ = 0; i_ < NPRE; ++i_) kpre[i_] = *(LAS const bf16x8*)(lds + koff + i_ * 32);
	v_add3_u32 v184, v172, v0, 0
	v_cvt_pk_bf16_f32 v125, v80, v81
	ds_read_b128 v[80:83], v184
	ds_read_b128 v[108:111], v184 offset:32
	v_cvt_pk_bf16_f32 v121, v78, v79
	v_cvt_pk_bf16_f32 v124, v74, v75
	v_cvt_pk_bf16_f32 v128, v76, v77
	s_waitcnt lgkmcnt(1)
	v_mfma_f32_32x32x16_bf16 v[64:79], v[80:83], v[116:119], 0
	v_mul_f32_e64 v48, v48, v194
	v_mul_f32_e64 v49, v49, v195
	v_mul_f32_e64 v24, v24, v190
	v_mul_f32_e64 v25, v25, v191
	v_mul_f32_e64 v2, v104, v48
	v_mul_f32_e64 v3, v105, v49
	v_pk_mul_f32 v[4:5], v[106:107], v[48:49]
	v_pk_fma_f32 v[2:3], v[106:107], v[40:41], v[2:3] neg_lo:[0,0,1] neg_hi:[0,0,1]
	v_pk_fma_f32 v[4:5], v[104:105], v[40:41], v[4:5]
	ds_read_b128 v[104:107], v184 offset:64
	s_waitcnt lgkmcnt(1)
	v_mfma_f32_32x32x16_bf16 v[64:79], v[108:111], v[120:123], v[64:79]
	v_mul_f32_e64 v22, v22, v42
	v_mul_f32_e64 v23, v23, v43
	v_mul_f32_e64 v16, v16, v38
	v_mul_f32_e64 v17, v17, v39
	v_mul_f32_e64 v28, v152, v24
	v_mul_f32_e64 v29, v153, v25
	v_pk_mul_f32 v[24:25], v[154:155], v[24:25]
	v_pk_mul_f32 v[20:21], v[20:21], v[36:37]
	v_pk_fma_f32 v[28:29], v[154:155], v[22:23], v[28:29]
	v_pk_fma_f32 v[22:23], v[152:153], v[22:23], v[24:25] neg_lo:[0,0,1] neg_hi:[0,0,1]
	v_pk_mul_f32 v[24:25], v[156:157], v[16:17]
	v_cvt_pk_bf16_f32 v151, v2, v3
	v_pk_fma_f32 v[24:25], v[148:149], v[20:21], v[24:25]
	v_pk_mul_f32 v[20:21], v[156:157], v[20:21]
	v_cvt_pk_bf16_f32 v129, v84, v85
	v_pk_fma_f32 v[0:1], v[148:149], v[16:17], v[20:21] neg_lo:[0,0,1] neg_hi:[0,0,1]
	v_pk_mul_f32 v[46:47], v[46:47], v[180:181]
	v_cvt_pk_bf16_f32 v148, v0, v1
	ds_read_b128 v[0:3], v184 offset:96
	s_waitcnt lgkmcnt(1)
	v_mfma_f32_32x32x16_bf16 v[64:79], v[104:107], v[124:127], v[64:79]
	v_mul_f32_e64 v44, v44, v178
	v_mul_f32_e64 v45, v45, v179
	v_mul_f32_e64 v6, v92, v46
	v_mul_f32_e64 v7, v93, v47
	v_mul_f32_e64 v8, v94, v46
	v_mul_f32_e64 v9, v95, v47
	v_pk_fma_f32 v[6:7], v[94:95], v[44:45], v[6:7] neg_lo:[0,0,1] neg_hi:[0,0,1]
	v_pk_fma_f32 v[8:9], v[92:93], v[44:45], v[8:9]
	v_mov_b32_e32 v48, 0
	v_cvt_pk_bf16_f32 v149, v18, v19
	s_waitcnt lgkmcnt(0)
	v_mfma_f32_32x32x16_bf16 v[64:79], v[0:3], v[128:131], v[64:79]
	v_cvt_pk_bf16_f32 v150, v56, v57
	v_cvt_pk_bf16_f32 v152, v24, v25
	v_cvt_pk_bf16_f32 v153, v30, v31
	v_cvt_pk_bf16_f32 v154, v54, v55
	v_cvt_pk_bf16_f32 v155, v4, v5
	v_cvt_pk_bf16_f32 v156, v22, v23
	v_cvt_pk_bf16_f32 v157, v26, v27
	v_cvt_pk_bf16_f32 v158, v52, v53
	v_cvt_pk_bf16_f32 v159, v6, v7
	v_cvt_pk_bf16_f32 v160, v28, v29
	v_cvt_pk_bf16_f32 v161, v34, v35
	v_cvt_pk_bf16_f32 v162, v60, v61
	v_cvt_pk_bf16_f32 v163, v8, v9
	v_mov_b32_e32 v174, v168
	v_mov_b32_e32 v176, v50
	s_add_u32 s98, s46, s14
	s_addc_u32 s99, s47, s15
	s_add_u32 s98, s98, 0x12310000
	s_addc_u32 s99, s99, 0
	s_add_u32 s100, s46, s42
	s_addc_u32 s101, s47, s43
	s_add_u32 s100, s100, 0x12f10000
	s_addc_u32 s101, s101, 0
	s_mov_b64 s[42:43], 0
	v_mov_b32_e32 v96, 0
	v_mov_b32_e32 v97, 0
	v_mov_b32_e32 v98, 0
	v_mov_b32_e32 v99, 0
	v_mov_b32_e32 v100, 0
	v_mov_b32_e32 v101, 0
	v_mov_b32_e32 v102, 0
	v_mov_b32_e32 v103, 0
	v_mov_b32_e32 v49, v48
	v_mov_b32_e32 v50, v48
	v_mov_b32_e32 v51, v48
	v_mov_b32_e32 v52, v48
	v_mov_b32_e32 v53, v48
	v_mov_b32_e32 v54, v48
	v_mov_b32_e32 v55, v48
	v_mov_b32_e32 v56, v48
	v_mov_b32_e32 v57, v48
	v_mov_b32_e32 v58, v48
	v_mov_b32_e32 v59, v48
	v_mov_b32_e32 v60, v48
	v_mov_b32_e32 v61, v48
	v_mov_b32_e32 v62, v48
	v_mov_b32_e32 v63, v48
	v_mov_b32_e32 v32, v48
	v_mov_b32_e32 v33, v48
	v_mov_b32_e32 v34, v48
	v_mov_b32_e32 v35, v48
	v_mov_b32_e32 v36, v48
	v_mov_b32_e32 v37, v48
	v_mov_b32_e32 v38, v48
	v_mov_b32_e32 v39, v48
	v_mov_b32_e32 v40, v48
	v_mov_b32_e32 v41, v48
	v_mov_b32_e32 v42, v48
	v_mov_b32_e32 v43, v48
	v_mov_b32_e32 v44, v48
	v_mov_b32_e32 v45, v48
	v_mov_b32_e32 v46, v48
	v_mov_b32_e32 v47, v48
	v_mov_b32_e32 v16, v48
	v_mov_b32_e32 v17, v48
	v_mov_b32_e32 v18, v48
	v_mov_b32_e32 v19, v48
	v_mov_b32_e32 v20, v48
	v_mov_b32_e32 v21, v48
	v_mov_b32_e32 v22, v48
	v_mov_b32_e32 v23, v48
	v_mov_b32_e32 v24, v48
	v_mov_b32_e32 v25, v48
	v_mov_b32_e32 v26, v48
	v_mov_b32_e32 v27, v48
	v_mov_b32_e32 v28, v48
	v_mov_b32_e32 v29, v48
	v_mov_b32_e32 v30, v48
	v_mov_b32_e32 v31, v48
	v_mov_b32_e32 v0, v48
	v_mov_b32_e32 v1, v48
	v_mov_b32_e32 v2, v48
	v_mov_b32_e32 v3, v48
	v_mov_b32_e32 v4, v48
	v_mov_b32_e32 v5, v48
	v_mov_b32_e32 v6, v48
	v_mov_b32_e32 v7, v48
	v_mov_b32_e32 v8, v48
	v_mov_b32_e32 v9, v48
	v_mov_b32_e32 v10, v48
	v_mov_b32_e32 v11, v48
	v_mov_b32_e32 v12, v48
	v_mov_b32_e32 v13, v48
	v_mov_b32_e32 v14, v48
	v_mov_b32_e32 v15, v48
	v_mov_b32_e32 v178, v48
	v_mov_b32_e32 v179, v48

.LBB0_439:
	s_cmpk_gt_u32 s33, 0xfb
	s_cbranch_scc1 .LBB0_441
	global_load_dwordx4 v[132:135], v174, s[98:99]
	global_load_dwordx4 v[136:139], v176, s[100:101]
	s_add_u32 s98, s98, 0x4000
	s_addc_u32 s99, s99, 0
	s_add_u32 s100, s100, 0x4000
	s_addc_u32 s101, s101, 0
.LBB0_441:
	s_and_b32 s48, s33, 2
	s_add_i32 s4, s33, -1
	s_and_b32 s49, s4, 3
	s_mul_i32 s4, s48, 0x4800
	v_add_u32_e32 v168, s4, v184
	s_cmp_eq_u32 s33, 0
	ds_read_b128 v[164:167], v168 offset:96
	s_cselect_b64 s[6:7], -1, 0
	s_mulk_i32 s49, 0x4800
	s_and_b64 s[4:5], s[6:7], exec
	s_cselect_b32 s4, 0, s49
	v_add_u32_e32 v84, s4, v184
	v_exp_f32_e32 v64, v64
	v_exp_f32_e32 v65, v65
	s_nop 0
	v_add_f32_e32 v113, v65, v64
	v_cvt_pk_bf16_f32 v112, v64, v65
	ds_read_b128 v[186:189], v84 offset:9280
	ds_read_b128 v[190:193], v84 offset:9312
	ds_read_b128 v[194:197], v84 offset:13888
	ds_read_b128 v[198:201], v84 offset:13920
	v_mfma_f32_32x32x16_bf16 v[80:95], v[80:83], v[148:151], 0
	v_exp_f32_e32 v64, v66
	v_exp_f32_e32 v65, v67
	v_add_f32_e32 v66, v64, v113
	v_add_f32_e32 v66, v65, v66
	v_cvt_pk_bf16_f32 v113, v64, v65
	v_mfma_f32_32x32x16_bf16 v[80:95], v[108:111], v[152:155], v[80:95]
	v_exp_f32_e32 v64, v68
	v_exp_f32_e32 v65, v69
	v_add_f32_e32 v66, v64, v66
	v_cvt_pk_bf16_f32 v114, v64, v65
	v_add_f32_e32 v64, v65, v66
	v_mfma_f32_32x32x16_bf16 v[80:95], v[104:107], v[156:159], v[80:95]
	v_exp_f32_e32 v65, v70
	v_exp_f32_e32 v66, v71
	v_add_f32_e32 v64, v65, v64
	v_cvt_pk_bf16_f32 v115, v65, v66
	v_add_f32_e32 v64, v66, v64
	s_waitcnt lgkmcnt(4)
	v_mfma_f32_32x32x16_bf16 v[80:95], v[164:167], v[160:163], v[80:95]
	v_exp_f32_e32 v65, v72
	v_exp_f32_e32 v66, v73
	v_add_f32_e32 v64, v65, v64
	v_cvt_pk_bf16_f32 v104, v65, v66
	v_add_f32_e32 v64, v66, v64
	s_waitcnt lgkmcnt(0)
	v_mfma_f32_32x32x16_bf16 v[16:31], v[186:189], v[96:99], v[16:31]
	v_exp_f32_e32 v65, v74
	v_exp_f32_e32 v66, v75
	v_add_f32_e32 v64, v65, v64
	v_cvt_pk_bf16_f32 v105, v65, v66
	v_add_f32_e32 v64, v66, v64
	v_mfma_f32_32x32x16_bf16 v[16:31], v[190:193], v[100:103], v[16:31]
	v_exp_f32_e32 v65, v76
	v_exp_f32_e32 v66, v77
	v_add_f32_e32 v64, v65, v64
	v_cvt_pk_bf16_f32 v106, v65, v66
	v_add_f32_e32 v64, v66, v64
	v_mfma_f32_32x32x16_bf16 v[0:15], v[194:197], v[96:99], v[0:15]
	v_exp_f32_e32 v65, v78
	v_exp_f32_e32 v66, v79
	v_add_f32_e32 v64, v65, v64
	v_cvt_pk_bf16_f32 v107, v65, v66
	v_add_f32_e32 v185, v66, v64
	v_exp_f32_e32 v68, v80
	v_exp_f32_e32 v69, v81
	s_nop 0
	v_add_f32_e32 v80, v69, v68
	v_cvt_pk_bf16_f32 v96, v68, v69
	v_mfma_f32_32x32x16_bf16 v[0:15], v[198:201], v[100:103], v[0:15]
	ds_read_b128 v[64:67], v168 offset:4608
	ds_read_b128 v[164:167], v168 offset:4640
	ds_read_b128 v[108:111], v168 offset:4672
	v_cmp_ge_f32_e32 vcc, s62, v185
	s_mov_b64 s[8:9], -1
	s_mov_b64 s[4:5], -1
	s_and_saveexec_b64 s[10:11], vcc
	v_cmp_gt_f32_e32 vcc, s75, v185
	s_and_b64 s[4:5], s[6:7], vcc
	s_orn2_b64 s[4:5], s[4:5], exec
	s_or_b64 exec, exec, s[10:11]
	ds_read_b128 v[186:189], v168 offset:4704
	s_waitcnt lgkmcnt(1)
	v_mfma_f32_32x32x16_bf16 v[64:79], v[64:67], v[116:119], 0
	ds_read_b128 v[190:193], v168 offset:9216
	ds_read_b128 v[194:197], v168 offset:9248
	ds_read_b128 v[198:201], v168 offset:13824
	ds_read_b128 v[230:233], v168 offset:13856
	v_exp_f32_e32 v81, v82
	v_exp_f32_e32 v82, v83
	v_add_f32_e32 v80, v81, v80
	v_add_f32_e32 v80, v82, v80
	v_cvt_pk_bf16_f32 v97, v81, v82
	v_mfma_f32_32x32x16_bf16 v[64:79], v[164:167], v[120:123], v[64:79]
	v_exp_f32_e32 v81, v84
	v_exp_f32_e32 v82, v85
	v_add_f32_e32 v80, v81, v80
	v_cvt_pk_bf16_f32 v98, v81, v82
	v_add_f32_e32 v80, v82, v80
	v_mfma_f32_32x32x16_bf16 v[64:79], v[108:111], v[124:127], v[64:79]
	v_exp_f32_e32 v81, v86
	v_exp_f32_e32 v82, v87
	v_add_f32_e32 v80, v81, v80
	v_cvt_pk_bf16_f32 v99, v81, v82
	v_add_f32_e32 v80, v82, v80
	s_waitcnt lgkmcnt(4)
	v_mfma_f32_32x32x16_bf16 v[64:79], v[186:189], v[128:131], v[64:79]
	v_exp_f32_e32 v81, v88
	v_exp_f32_e32 v82, v89
	v_add_f32_e32 v80, v81, v80
	v_cvt_pk_bf16_f32 v100, v81, v82
	v_add_f32_e32 v80, v82, v80
	s_waitcnt lgkmcnt(0)
	v_mfma_f32_32x32x16_bf16 v[48:63], v[190:193], v[112:115], v[48:63]
	v_exp_f32_e32 v81, v90
	v_exp_f32_e32 v82, v91
	v_add_f32_e32 v80, v81, v80
	v_cvt_pk_bf16_f32 v101, v81, v82
	v_add_f32_e32 v80, v82, v80
	v_mfma_f32_32x32x16_bf16 v[48:63], v[194:197], v[104:107], v[48:63]
	v_exp_f32_e32 v81, v92
	v_exp_f32_e32 v82, v93
	v_add_f32_e32 v80, v81, v80
	v_cvt_pk_bf16_f32 v102, v81, v82
	v_add_f32_e32 v80, v82, v80
	v_mfma_f32_32x32x16_bf16 v[32:47], v[198:201], v[112:115], v[32:47]
	v_exp_f32_e32 v81, v94
	v_exp_f32_e32 v82, v95
	v_add_f32_e32 v80, v81, v80
	v_cvt_pk_bf16_f32 v103, v81, v82
	v_add_f32_e32 v164, v82, v80
	v_exp_f32_e32 v64, v64
	v_exp_f32_e32 v65, v65
	s_nop 0
	v_add_f32_e32 v165, v65, v64
	v_cvt_pk_bf16_f32 v186, v64, v65
	v_mfma_f32_32x32x16_bf16 v[32:47], v[230:233], v[104:107], v[32:47]
	ds_read_b128 v[80:83], v168 offset:4608
	ds_read_b128 v[112:115], v168 offset:4640
	ds_read_b128 v[108:111], v168 offset:4672
	v_cndmask_b32_e64 v84, 0, 1, s[4:5]
	v_cmp_ne_u32_e64 s[4:5], 0, v84
	v_cmp_ge_f32_e32 vcc, s62, v164
	s_and_saveexec_b64 s[10:11], vcc
	v_cmp_gt_f32_e32 vcc, s75, v164
	s_and_b64 s[6:7], s[6:7], vcc
	s_orn2_b64 s[8:9], s[6:7], exec
	s_or_b64 exec, exec, s[10:11]
	v_cndmask_b32_e64 v84, 0, 1, s[8:9]
	v_cmp_ne_u32_e64 s[6:7], 0, v84
	ds_read_b128 v[104:107], v168 offset:4704
	s_waitcnt lgkmcnt(1)
	v_mfma_f32_32x32x16_bf16 v[80:95], v[80:83], v[148:151], 0
	ds_read_b128 v[190:193], v168 offset:9216
	ds_read_b128 v[194:197], v168 offset:9248
	ds_read_b128 v[198:201], v168 offset:13824
	ds_read_b128 v[230:233], v168 offset:13856
	v_exp_f32_e32 v64, v66
	v_exp_f32_e32 v65, v67
	v_add_f32_e32 v66, v64, v165
	v_add_f32_e32 v66, v65, v66
	v_cvt_pk_bf16_f32 v187, v64, v65
	v_mfma_f32_32x32x16_bf16 v[80:95], v[112:115], v[152:155], v[80:95]
	v_exp_f32_e32 v64, v68
	v_exp_f32_e32 v65, v69
	v_add_f32_e32 v66, v64, v66
	v_cvt_pk_bf16_f32 v188, v64, v65
	v_add_f32_e32 v64, v65, v66
	v_mfma_f32_32x32x16_bf16 v[80:95], v[108:111], v[156:159], v[80:95]
	v_exp_f32_e32 v65, v70
	v_exp_f32_e32 v66, v71
	v_add_f32_e32 v64, v65, v64
	v_cvt_pk_bf16_f32 v189, v65, v66
	v_add_f32_e32 v64, v66, v64
	s_waitcnt lgkmcnt(4)
	v_mfma_f32_32x32x16_bf16 v[80:95], v[104:107], v[160:163], v[80:95]
	v_exp_f32_e32 v65, v72
	v_exp_f32_e32 v66, v73
	v_add_f32_e32 v64, v65, v64
	v_cvt_pk_bf16_f32 v108, v65, v66
	v_add_f32_e32 v64, v66, v64
	s_waitcnt lgkmcnt(0)
	v_mfma_f32_32x32x16_bf16 v[16:31], v[190:193], v[96:99], v[16:31]
	v_exp_f32_e32 v65, v74
	v_exp_f32_e32 v66, v75
	v_add_f32_e32 v64, v65, v64
	v_cvt_pk_bf16_f32 v109, v65, v66
	v_add_f32_e32 v64, v66, v64
	v_mfma_f32_32x32x16_bf16 v[16:31], v[194:197], v[100:103], v[16:31]
	v_exp_f32_e32 v65, v76
	v_exp_f32_e32 v66, v77
	v_add_f32_e32 v64, v65, v64
	v_cvt_pk_bf16_f32 v110, v65, v66
	v_add_f32_e32 v64, v66, v64
	v_mfma_f32_32x32x16_bf16 v[0:15], v[198:201], v[96:99], v[0:15]
	v_exp_f32_e32 v65, v78
	v_exp_f32_e32 v66, v79
	v_add_f32_e32 v64, v65, v64
	v_cvt_pk_bf16_f32 v111, v65, v66
	v_add_f32_e32 v104, v66, v64
	v_exp_f32_e32 v68, v80
	v_exp_f32_e32 v69, v81
	s_nop 0
	v_add_f32_e32 v81, v69, v68
	v_cvt_pk_bf16_f32 v80, v68, v69
	v_mfma_f32_32x32x16_bf16 v[0:15], v[230:233], v[100:103], v[0:15]
	ds_read_b128 v[64:67], v168 offset:18432
	ds_read_b128 v[96:99], v168 offset:18464
	ds_read_b128 v[112:115], v168 offset:18496
	v_cmp_nge_f32_e64 s[8:9], s62, v104
	ds_read_b128 v[100:103], v168 offset:18528
	s_waitcnt lgkmcnt(1)
	v_mfma_f32_32x32x16_bf16 v[64:79], v[64:67], v[116:119], 0
	ds_read_b128 v[190:193], v168 offset:9280
	ds_read_b128 v[194:197], v168 offset:9312
	ds_read_b128 v[198:201], v168 offset:13888
	ds_read_b128 v[230:233], v168 offset:13920
	v_exp_f32_e32 v82, v82
	v_exp_f32_e32 v83, v83
	v_add_f32_e32 v81, v82, v81
	v_add_f32_e32 v105, v83, v81
	v_cvt_pk_bf16_f32 v81, v82, v83
	v_mfma_f32_32x32x16_bf16 v[64:79], v[96:99], v[120:123], v[64:79]
	v_exp_f32_e32 v82, v84
	v_exp_f32_e32 v83, v85
	v_add_f32_e32 v84, v82, v105
	v_cvt_pk_bf16_f32 v82, v82, v83
	v_add_f32_e32 v83, v83, v84
	v_mfma_f32_32x32x16_bf16 v[64:79], v[112:115], v[124:127], v[64:79]
	v_exp_f32_e32 v84, v86
	v_exp_f32_e32 v85, v87
	v_add_f32_e32 v86, v84, v83
	v_cvt_pk_bf16_f32 v83, v84, v85
	v_add_f32_e32 v84, v85, v86
	s_waitcnt lgkmcnt(4)
	v_mfma_f32_32x32x16_bf16 v[64:79], v[100:103], v[128:131], v[64:79]
	v_exp_f32_e32 v85, v88
	v_exp_f32_e32 v86, v89
	v_add_f32_e32 v87, v85, v84
	v_cvt_pk_bf16_f32 v84, v85, v86
	v_add_f32_e32 v85, v86, v87
	s_waitcnt lgkmcnt(0)
	v_mfma_f32_32x32x16_bf16 v[48:63], v[190:193], v[186:189], v[48:63]
	v_exp_f32_e32 v86, v90
	v_exp_f32_e32 v87, v91
	v_add_f32_e32 v88, v86, v85
	v_cvt_pk_bf16_f32 v85, v86, v87
	v_add_f32_e32 v86, v87, v88
	v_mfma_f32_32x32x16_bf16 v[48:63], v[194:197], v[108:111], v[48:63]
	v_exp_f32_e32 v87, v92
	v_exp_f32_e32 v88, v93
	v_add_f32_e32 v89, v87, v86
	v_cvt_pk_bf16_f32 v86, v87, v88
	v_add_f32_e32 v87, v88, v89
	v_mfma_f32_32x32x16_bf16 v[32:47], v[198:201], v[186:189], v[32:47]
	v_exp_f32_e32 v88, v94
	v_exp_f32_e32 v89, v95
	v_add_f32_e32 v90, v88, v87
	v_cvt_pk_bf16_f32 v87, v88, v89
	v_add_f32_e32 v105, v89, v90
	v_mfma_f32_32x32x16_bf16 v[32:47], v[230:233], v[108:111], v[32:47]
	ds_read_b128 v[96:99], v168 offset:18432
	ds_read_b128 v[92:95], v168 offset:18464
	ds_read_b128 v[88:91], v168 offset:18496
	v_cmp_nge_f32_e64 s[10:11], s62, v105
	s_waitcnt lgkmcnt(0)
	s_barrier
	s_cmpk_gt_u32 s33, 0xfc
	s_cbranch_scc1 .LBB0_447
	v_add_u32_e32 v100, s49, v173
	s_waitcnt vmcnt(1)
	ds_write_b128 v100, v[140:143]
	s_waitcnt vmcnt(0)
	ds_write_b128 v100, v[144:147] offset:9216
.LBB0_447:
	s_cmpk_gt_u32 s33, 0xfa
	s_cbranch_scc1 .LBB0_449
	global_load_dwordx4 v[140:143], v174, s[98:99]
	global_load_dwordx4 v[144:147], v176, s[100:101]
	s_add_u32 s98, s98, 0x4000
	s_addc_u32 s99, s99, 0
	s_add_u32 s100, s100, 0x4000
	s_addc_u32 s101, s101, 0
.LBB0_449:
	v_add_f32_e32 v101, v179, v164
	ds_read_b128 v[164:167], v168 offset:18528
	s_or_b64 s[4:5], s[6:7], s[4:5]
	v_add_f32_e32 v100, v178, v185
	s_or_b64 s[4:5], s[4:5], s[8:9]
	s_or_b64 s[4:5], s[4:5], s[10:11]
	v_pk_add_f32 v[182:183], v[100:101], v[104:105]
	s_xor_b32 s8, s48, 2
	v_exp_f32_e32 v64, v64
	v_exp_f32_e32 v65, v65
	s_nop 0
	v_add_f32_e32 v185, v65, v64
	v_cvt_pk_bf16_f32 v64, v64, v65
	v_mfma_f32_32x32x16_bf16 v[100:115], v[96:99], v[148:151], 0
	ds_read_b128 v[178:181], v168 offset:9280
	ds_read_b128 v[186:189], v168 offset:9312
	ds_read_b128 v[190:193], v168 offset:13888
	ds_read_b128 v[194:197], v168 offset:13920
	v_exp_f32_e32 v65, v66
	v_exp_f32_e32 v66, v67
	v_add_f32_e32 v67, v65, v185
	v_add_f32_e32 v67, v66, v67
	v_cvt_pk_bf16_f32 v65, v65, v66
	v_mfma_f32_32x32x16_bf16 v[100:115], v[92:95], v[152:155], v[100:115]
	v_exp_f32_e32 v66, v68
	v_exp_f32_e32 v68, v69
	v_add_f32_e32 v67, v66, v67
	v_cvt_pk_bf16_f32 v66, v66, v68
	v_add_f32_e32 v67, v68, v67
	v_mfma_f32_32x32x16_bf16 v[100:115], v[88:91], v[156:159], v[100:115]
	v_exp_f32_e32 v68, v70
	v_exp_f32_e32 v69, v71
	v_add_f32_e32 v70, v68, v67
	v_cvt_pk_bf16_f32 v67, v68, v69
	v_add_f32_e32 v68, v69, v70
	s_waitcnt lgkmcnt(4)
	v_mfma_f32_32x32x16_bf16 v[100:115], v[164:167], v[160:163], v[100:115]
	v_exp_f32_e32 v69, v72
	v_exp_f32_e32 v70, v73
	v_add_f32_e32 v71, v69, v68
	v_cvt_pk_bf16_f32 v68, v69, v70
	v_add_f32_e32 v69, v70, v71
	s_waitcnt lgkmcnt(0)
	v_mfma_f32_32x32x16_bf16 v[16:31], v[178:181], v[80:83], v[16:31]
	v_exp_f32_e32 v70, v74
	v_exp_f32_e32 v71, v75
	v_add_f32_e32 v72, v70, v69
	v_cvt_pk_bf16_f32 v69, v70, v71
	v_add_f32_e32 v70, v71, v72
	v_mfma_f32_32x32x16_bf16 v[16:31], v[186:189], v[84:87], v[16:31]
	v_exp_f32_e32 v71, v76
	v_exp_f32_e32 v72, v77
	v_add_f32_e32 v73, v71, v70
	v_cvt_pk_bf16_f32 v70, v71, v72
	v_add_f32_e32 v71, v72, v73
	v_mfma_f32_32x32x16_bf16 v[0:15], v[190:193], v[80:83], v[0:15]
	v_exp_f32_e32 v72, v78
	v_exp_f32_e32 v73, v79
	v_add_f32_e32 v74, v72, v71
	v_cvt_pk_bf16_f32 v71, v72, v73
	v_add_f32_e32 v198, v73, v74
	v_exp_f32_e32 v88, v100
	v_exp_f32_e32 v89, v101
	s_nop 0
	v_add_f32_e32 v165, v89, v88
	v_cvt_pk_bf16_f32 v164, v88, v89
	v_mfma_f32_32x32x16_bf16 v[0:15], v[194:197], v[84:87], v[0:15]
	ds_read_b128 v[72:75], v168 offset:23040
	ds_read_b128 v[76:79], v168 offset:23072
	ds_read_b128 v[80:83], v168 offset:23104
	v_cmp_nge_f32_e32 vcc, s62, v198
	ds_read_b128 v[84:87], v168 offset:23136
	v_exp_f32_e32 v166, v102
	v_exp_f32_e32 v167, v103
	s_waitcnt lgkmcnt(1)
	v_mfma_f32_32x32x16_bf16 v[88:103], v[72:75], v[116:119], 0
	ds_read_b128 v[178:181], v168 offset:27648
	ds_read_b128 v[186:189], v168 offset:27680
	ds_read_b128 v[190:193], v168 offset:32256
	ds_read_b128 v[194:197], v168 offset:32288
	v_add_f32_e32 v72, v166, v165
	v_add_f32_e32 v72, v167, v72
	v_cvt_pk_bf16_f32 v165, v166, v167
	v_mfma_f32_32x32x16_bf16 v[88:103], v[76:79], v[120:123], v[88:103]
	v_exp_f32_e32 v73, v104
	v_exp_f32_e32 v74, v105
	v_add_f32_e32 v72, v73, v72
	v_cvt_pk_bf16_f32 v166, v73, v74
	v_add_f32_e32 v72, v74, v72
	v_mfma_f32_32x32x16_bf16 v[88:103], v[80:83], v[124:127], v[88:103]
	v_exp_f32_e32 v73, v106
	v_exp_f32_e32 v74, v107
	v_add_f32_e32 v72, v73, v72
	v_cvt_pk_bf16_f32 v167, v73, v74
	v_add_f32_e32 v72, v74, v72
	s_waitcnt lgkmcnt(4)
	v_mfma_f32_32x32x16_bf16 v[88:103], v[84:87], v[128:131], v[88:103]
	v_exp_f32_e32 v73, v108
	v_exp_f32_e32 v74, v109
	v_add_f32_e32 v75, v73, v72
	v_cvt_pk_bf16_f32 v72, v73, v74
	v_add_f32_e32 v73, v74, v75
	s_waitcnt lgkmcnt(0)
	v_mfma_f32_32x32x16_bf16 v[48:63], v[178:181], v[64:67], v[48:63]
	v_exp_f32_e32 v74, v110
	v_exp_f32_e32 v75, v111
	v_add_f32_e32 v76, v74, v73
	v_cvt_pk_bf16_f32 v73, v74, v75
	v_add_f32_e32 v74, v75, v76
	v_mfma_f32_32x32x16_bf16 v[48:63], v[186:189], v[68:71], v[48:63]
	v_exp_f32_e32 v75, v112
	v_exp_f32_e32 v76, v113
	v_add_f32_e32 v77, v75, v74
	v_cvt_pk_bf16_f32 v74, v75, v76
	v_add_f32_e32 v75, v76, v77
	v_mfma_f32_32x32x16_bf16 v[32:47], v[190:193], v[64:67], v[32:47]
	v_exp_f32_e32 v76, v114
	v_exp_f32_e32 v77, v115
	v_add_f32_e32 v78, v76, v75
	v_cvt_pk_bf16_f32 v75, v76, v77
	v_add_f32_e32 v199, v77, v78
	v_exp_f32_e32 v76, v88
	v_exp_f32_e32 v77, v89
	s_nop 0
	v_add_f32_e32 v113, v77, v76
	v_cvt_pk_bf16_f32 v112, v76, v77
	v_mfma_f32_32x32x16_bf16 v[32:47], v[194:197], v[68:71], v[32:47]
	ds_read_b128 v[64:67], v168 offset:23040
	ds_read_b128 v[104:107], v168 offset:23072
	ds_read_b128 v[108:111], v168 offset:23104
	s_or_b64 s[6:7], s[4:5], vcc
	v_cmp_nge_f32_e32 vcc, s62, v199
	v_pk_add_f32 v[182:183], v[182:183], v[198:199]
	ds_read_b128 v[68:71], v168 offset:23136
	v_exp_f32_e32 v114, v90
	v_exp_f32_e32 v115, v91
	s_waitcnt lgkmcnt(1)
; #define LAS __attribute__((address_space(3)))
; template <int MODE, bool FAST> __device__ __forceinline__ bool attn_unit(LAS unsigned char* lds, const AttU& U, const int wv) {
;     ...
;     pb[1][0] = (bf16x8){0, 0, 0, 0, 0, 0, 0, 0}; pb[1][1] = pb[1][0];
;     ATT_QK(0, 0, 0);
;     bf16x8 kpre[NPRE > 0 ? NPRE : 1];
; #pragma unroll
;     for (int i_ = 0; i_ < NPRE; ++i_) kpre[i_] = *(LAS const bf16x8*)(lds + koff + i_ * 32);
;     ...
;     if constexpr (FAST) {
;         for (int t2 = U.kt0; t2 < U.kt1; t2 += 2) { ATT_TILE(t2, 4, rk, rr, rv); ATT_TILE(t2 + 1, 4, rk2, rr2, rv2); }
	v_mfma_f32_32x32x16_bf16 v[76:91], v[64:67], v[148:151], 0
	ds_read_b128 v[178:181], v168 offset:27648
	ds_read_b128 v[186:189], v168 offset:27680
	ds_read_b128 v[190:193], v168 offset:32256
	ds_read_b128 v[194:197], v168 offset:32288
	v_add_f32_e32 v64, v114, v113
	v_add_f32_e32 v64, v115, v64
	v_cvt_pk_bf16_f32 v113, v114, v115
	v_mfma_f32_32x32x16_bf16 v[76:91], v[104:107], v[152:155], v[76:91]
	v_exp_f32_e32 v65, v92
	v_exp_f32_e32 v66, v93
	v_add_f32_e32 v64, v65, v64
	v_cvt_pk_bf16_f32 v114, v65, v66
	v_add_f32_e32 v64, v66, v64
	v_mfma_f32_32x32x16_bf16 v[76:91], v[108:111], v[156:159], v[76:91]
	v_exp_f32_e32 v65, v94
	v_exp_f32_e32 v66, v95
	v_add_f32_e32 v64, v65, v64
	v_cvt_pk_bf16_f32 v115, v65, v66
	v_add_f32_e32 v64, v66, v64
	s_waitcnt lgkmcnt(4)
	v_mfma_f32_32x32x16_bf16 v[76:91], v[68:71], v[160:163], v[76:91]
	v_exp_f32_e32 v65, v96
	v_exp_f32_e32 v66, v97
	v_add_f32_e32 v64, v65, v64
	v_cvt_pk_bf16_f32 v92, v65, v66
	v_add_f32_e32 v64, v66, v64
	s_waitcnt lgkmcnt(0)
	v_mfma_f32_32x32x16_bf16 v[16:31], v[178:181], v[164:167], v[16:31]
	v_exp_f32_e32 v65, v98
	v_exp_f32_e32 v66, v99
	v_add_f32_e32 v64, v65, v64
	v_cvt_pk_bf16_f32 v93, v65, v66
	v_add_f32_e32 v64, v66, v64
	v_mfma_f32_32x32x16_bf16 v[16:31], v[186:189], v[72:75], v[16:31]
	v_exp_f32_e32 v65, v100
	v_exp_f32_e32 v66, v101
	v_add_f32_e32 v64, v65, v64
	v_cvt_pk_bf16_f32 v94, v65, v66
	v_add_f32_e32 v64, v66, v64
	v_mfma_f32_32x32x16_bf16 v[0:15], v[190:193], v[164:167], v[0:15]
	v_exp_f32_e32 v65, v102
	v_exp_f32_e32 v66, v103
	v_add_f32_e32 v64, v65, v64
	v_cvt_pk_bf16_f32 v95, v65, v66
	v_add_f32_e32 v198, v66, v64
	s_mulk_i32 s8, 0x4800
	v_exp_f32_e32 v68, v76
	v_exp_f32_e32 v69, v77
	s_nop 0
	v_add_f32_e32 v97, v69, v68
	v_cvt_pk_bf16_f32 v96, v68, v69
	v_mfma_f32_32x32x16_bf16 v[0:15], v[194:197], v[72:75], v[0:15]
	v_add_u32_e32 v185, s8, v184
	ds_read_b128 v[64:67], v185
	ds_read_b128 v[100:103], v185 offset:32
	ds_read_b128 v[104:107], v185 offset:64
	v_cmp_nge_f32_e64 s[4:5], s62, v198
	ds_read_b128 v[108:111], v185 offset:96
	s_or_b64 s[6:7], s[6:7], vcc
	v_exp_f32_e32 v98, v78
	v_exp_f32_e32 v99, v79
	s_waitcnt lgkmcnt(1)
	v_mfma_f32_32x32x16_bf16 v[64:79], v[64:67], v[116:119], 0
	ds_read_b128 v[164:167], v168 offset:27712
	ds_read_b128 v[178:181], v168 offset:27744
	ds_read_b128 v[186:189], v168 offset:32320
	ds_read_b128 v[190:193], v168 offset:32352
	v_add_f32_e32 v97, v98, v97
	v_add_f32_e32 v168, v99, v97
	v_cvt_pk_bf16_f32 v97, v98, v99
	v_mfma_f32_32x32x16_bf16 v[64:79], v[100:103], v[120:123], v[64:79]
	v_exp_f32_e32 v80, v80
	v_exp_f32_e32 v81, v81
	v_add_f32_e32 v99, v80, v168
	v_cvt_pk_bf16_f32 v98, v80, v81
	v_add_f32_e32 v80, v81, v99
	v_mfma_f32_32x32x16_bf16 v[64:79], v[104:107], v[124:127], v[64:79]
	v_exp_f32_e32 v81, v82
	v_exp_f32_e32 v82, v83
	v_add_f32_e32 v80, v81, v80
	v_cvt_pk_bf16_f32 v99, v81, v82
	v_add_f32_e32 v80, v82, v80
	s_waitcnt lgkmcnt(4)
	v_mfma_f32_32x32x16_bf16 v[64:79], v[108:111], v[128:131], v[64:79]
	v_exp_f32_e32 v81, v84
	v_exp_f32_e32 v82, v85
	v_add_f32_e32 v80, v81, v80
	v_cvt_pk_bf16_f32 v100, v81, v82
	v_add_f32_e32 v80, v82, v80
	s_waitcnt lgkmcnt(0)
	v_mfma_f32_32x32x16_bf16 v[48:63], v[164:167], v[112:115], v[48:63]
	v_exp_f32_e32 v81, v86
	v_exp_f32_e32 v82, v87
	v_add_f32_e32 v80, v81, v80
	v_cvt_pk_bf16_f32 v101, v81, v82
	v_add_f32_e32 v80, v82, v80
	v_mfma_f32_32x32x16_bf16 v[48:63], v[178:181], v[92:95], v[48:63]
	v_exp_f32_e32 v81, v88
	v_exp_f32_e32 v82, v89
	v_add_f32_e32 v80, v81, v80
	v_cvt_pk_bf16_f32 v102, v81, v82
	v_add_f32_e32 v80, v82, v80
	v_mfma_f32_32x32x16_bf16 v[32:47], v[186:189], v[112:115], v[32:47]
	v_exp_f32_e32 v81, v90
	v_exp_f32_e32 v82, v91
	v_add_f32_e32 v80, v81, v80
	v_cvt_pk_bf16_f32 v103, v81, v82
	v_add_f32_e32 v199, v82, v80
	v_mfma_f32_32x32x16_bf16 v[32:47], v[190:193], v[92:95], v[32:47]
	ds_read_b128 v[80:83], v185
	ds_read_b128 v[108:111], v185 offset:32
	ds_read_b128 v[104:107], v185 offset:64
	s_or_b64 s[4:5], s[6:7], s[4:5]
	v_cmp_nge_f32_e32 vcc, s62, v199
	s_or_b64 s[4:5], s[4:5], vcc
	s_cmp_lg_u64 s[4:5], 0
	s_cselect_b64 s[4:5], -1, 0
	s_or_b64 s[42:43], s[42:43], s[4:5]
	v_pk_add_f32 v[178:179], v[182:183], v[198:199]
	s_waitcnt lgkmcnt(0)
	s_barrier
	s_add_u32 s46, s46, 0x8000
	s_addc_u32 s47, s47, 0
	s_and_b64 vcc, exec, s[44:45]
	s_cbranch_vccnz .LBB0_451
	s_mov_b32 s33, s14
	s_branch .LBB0_437

.LBB0_927:
	s_add_i32 s6, s61, -1
	s_and_b32 s77, s61, 2
	s_and_b32 s79, s6, 3
	s_cmp_eq_u32 s61, 0
	s_cselect_b64 s[8:9], -1, 0
	s_mulk_i32 s79, 0x5800
	s_and_b64 s[6:7], s[8:9], exec
	s_mul_i32 s78, s77, 0x5800
	s_cselect_b32 s6, 0, s79
	s_add_i32 s76, s78, 0
	v_add_u32_e32 v199, s76, v241
	v_add_u32_e32 v210, s6, v244
	v_exp_f32_e32 v64, v64
	v_exp_f32_e32 v65, v65
	s_nop 0
	v_add_f32_e32 v84, v65, v64
	v_cvt_pk_bf16_f32 v178, v64, v65
	v_exp_f32_e32 v64, v66
	ds_read_b128 v[182:185], v199 offset:96
	ds_read_b128 v[246:249], v199 offset:128
	ds_read_b128 v[250:253], v199 offset:160
	v_exp_f32_e32 v65, v67
	v_add_f32_e32 v66, v64, v84
	v_mfma_f32_32x32x16_bf16 v[80:95], v[80:83], v[122:125], 0
	v_add_f32_e32 v66, v65, v66
	v_cvt_pk_bf16_f32 v179, v64, v65
	v_mfma_f32_32x32x16_bf16 v[80:95], v[174:177], v[126:129], v[80:95]
	v_exp_f32_e32 v64, v68
	v_exp_f32_e32 v65, v69
	v_add_f32_e32 v66, v64, v66
	v_add_f32_e32 v66, v65, v66
	v_cvt_pk_bf16_f32 v180, v64, v65
	v_mfma_f32_32x32x16_bf16 v[80:95], v[170:173], v[130:133], v[80:95]
	v_exp_f32_e32 v64, v70
	v_exp_f32_e32 v65, v71
	v_add_f32_e32 v66, v64, v66
	v_add_f32_e32 v170, v65, v66
	v_cvt_pk_bf16_f32 v181, v64, v65
	s_waitcnt lgkmcnt(0)
	v_mfma_f32_32x32x16_bf16 v[80:95], v[182:185], v[134:137], v[80:95]
	ds_read_b128 v[64:67], v210 offset:13376
	ds_read_b128 v[68:71], v210 offset:13408
	ds_read_b128 v[174:177], v210 offset:17984
	ds_read_b128 v[218:221], v210 offset:18016
	v_exp_f32_e32 v72, v72
	v_exp_f32_e32 v73, v73
	v_add_f32_e32 v170, v72, v170
	v_add_f32_e32 v171, v73, v170
	v_cvt_pk_bf16_f32 v170, v72, v73
	v_mfma_f32_32x32x16_bf16 v[80:95], v[246:249], v[154:157], v[80:95]
	v_exp_f32_e32 v72, v74
	v_exp_f32_e32 v73, v75
	v_add_f32_e32 v74, v72, v171
	v_add_f32_e32 v74, v73, v74
	v_cvt_pk_bf16_f32 v171, v72, v73
	v_mfma_f32_32x32x16_bf16 v[80:95], v[250:253], v[158:161], v[80:95]
	v_exp_f32_e32 v72, v76
	v_exp_f32_e32 v73, v77
	v_add_f32_e32 v74, v72, v74
	v_add_f32_e32 v74, v73, v74
	v_cvt_pk_bf16_f32 v172, v72, v73
	s_waitcnt lgkmcnt(0)
	v_mfma_f32_32x32x16_bf16 v[16:31], v[64:67], v[162:165], v[16:31]
	v_exp_f32_e32 v64, v78
	v_exp_f32_e32 v65, v79
	v_add_f32_e32 v66, v64, v74
	v_add_f32_e32 v246, v65, v66
	v_cvt_pk_bf16_f32 v173, v64, v65
	v_mfma_f32_32x32x16_bf16 v[0:15], v[174:177], v[162:165], v[0:15]
	ds_read_b128 v[64:67], v199 offset:6656
	ds_read_b128 v[182:185], v199 offset:6688
	ds_read_b128 v[174:177], v199 offset:6720
	v_cmp_ge_f32_e32 vcc, s48, v246
	s_mov_b64 s[10:11], -1
	s_mov_b64 s[6:7], -1
	v_mfma_f32_32x32x16_bf16 v[16:31], v[68:71], v[166:169], v[16:31]
	v_exp_f32_e32 v68, v80
	v_exp_f32_e32 v69, v81
	s_nop 0
	v_add_f32_e32 v70, v69, v68
	v_cvt_pk_bf16_f32 v162, v68, v69
	v_exp_f32_e32 v80, v82
	v_exp_f32_e32 v81, v83
	v_add_f32_e32 v82, v80, v70
	v_mfma_f32_32x32x16_bf16 v[0:15], v[218:221], v[166:169], v[0:15]
	s_and_saveexec_b64 s[12:13], vcc
	v_cmp_gt_f32_e32 vcc, s49, v246
	s_and_b64 s[6:7], s[8:9], vcc
	s_orn2_b64 s[6:7], s[6:7], exec
	s_or_b64 exec, exec, s[12:13]
	v_add_u32_e32 v211, s76, v243
	ds_read_b128 v[166:169], v199 offset:6752
	ds_read_b128 v[218:221], v199 offset:6784
	ds_read_b128 v[248:251], v199 offset:6816
	s_waitcnt lgkmcnt(3)
	v_mfma_f32_32x32x16_bf16 v[64:79], v[64:67], v[98:101], 0
	v_add_f32_e32 v82, v81, v82
	v_cvt_pk_bf16_f32 v163, v80, v81
	v_mfma_f32_32x32x16_bf16 v[64:79], v[182:185], v[102:105], v[64:79]
	v_exp_f32_e32 v80, v84
	v_exp_f32_e32 v81, v85
	v_add_f32_e32 v82, v80, v82
	v_add_f32_e32 v82, v81, v82
	v_cvt_pk_bf16_f32 v164, v80, v81
	v_mfma_f32_32x32x16_bf16 v[64:79], v[174:177], v[106:109], v[64:79]
	v_exp_f32_e32 v80, v86
	v_exp_f32_e32 v81, v87
	v_add_f32_e32 v82, v80, v82
	v_add_f32_e32 v174, v81, v82
	v_cvt_pk_bf16_f32 v165, v80, v81
	s_waitcnt lgkmcnt(0)
	v_mfma_f32_32x32x16_bf16 v[64:79], v[166:169], v[110:113], v[64:79]
	ds_read_b128 v[80:83], v211 offset:13312
	ds_read_b128 v[84:87], v211 offset:13344
	ds_read_b128 v[182:185], v211 offset:17920
	ds_read_b128 v[222:225], v211 offset:17952
	v_exp_f32_e32 v88, v88
	v_exp_f32_e32 v89, v89
	v_add_f32_e32 v166, v88, v174
	v_add_f32_e32 v166, v89, v166
	v_cvt_pk_bf16_f32 v174, v88, v89
	v_mfma_f32_32x32x16_bf16 v[64:79], v[218:221], v[114:117], v[64:79]
	v_exp_f32_e32 v88, v90
	v_exp_f32_e32 v89, v91
	v_add_f32_e32 v90, v88, v166
	v_add_f32_e32 v90, v89, v90
	v_cvt_pk_bf16_f32 v175, v88, v89
	v_mfma_f32_32x32x16_bf16 v[64:79], v[248:251], v[118:121], v[64:79]
	v_exp_f32_e32 v88, v92
	v_exp_f32_e32 v89, v93
	v_add_f32_e32 v90, v88, v90
	v_add_f32_e32 v90, v89, v90
	v_cvt_pk_bf16_f32 v176, v88, v89
	s_waitcnt lgkmcnt(0)
	v_mfma_f32_32x32x16_bf16 v[48:63], v[80:83], v[178:181], v[48:63]
	v_exp_f32_e32 v80, v94
	v_exp_f32_e32 v81, v95
	v_add_f32_e32 v82, v80, v90
	v_add_f32_e32 v247, v81, v82
	v_cvt_pk_bf16_f32 v177, v80, v81
	v_mfma_f32_32x32x16_bf16 v[32:47], v[182:185], v[178:181], v[32:47]
	ds_read_b128 v[80:83], v199 offset:6656
	ds_read_b128 v[182:185], v199 offset:6688
	ds_read_b128 v[178:181], v199 offset:6720
	v_cmp_ge_f32_e32 vcc, s48, v247
	v_mfma_f32_32x32x16_bf16 v[48:63], v[84:87], v[170:173], v[48:63]
	v_exp_f32_e32 v64, v64
	v_exp_f32_e32 v65, v65
	s_nop 0
	v_add_f32_e32 v84, v65, v64
	v_cvt_pk_bf16_f32 v166, v64, v65
	v_exp_f32_e32 v64, v66
	v_exp_f32_e32 v65, v67
	v_add_f32_e32 v66, v64, v84
	v_mfma_f32_32x32x16_bf16 v[32:47], v[222:225], v[170:173], v[32:47]
	s_and_saveexec_b64 s[12:13], vcc
	v_cmp_gt_f32_e32 vcc, s49, v247
	s_and_b64 s[8:9], s[8:9], vcc
	s_orn2_b64 s[10:11], s[8:9], exec
	s_or_b64 exec, exec, s[12:13]
	s_mov_b64 s[8:9], s[10:11]
	ds_read_b128 v[170:173], v199 offset:6752
	ds_read_b128 v[218:221], v199 offset:6784
	ds_read_b128 v[222:225], v199 offset:6816
	s_waitcnt lgkmcnt(3)
; #define LAS __attribute__((address_space(3)))
; template <int MODE, bool FAST> __device__ __forceinline__ bool attn_unit(LAS unsigned char* lds, const AttU& U, const int wv) {
;     ...
;     pb[1][0] = (bf16x8){0, 0, 0, 0, 0, 0, 0, 0}; pb[1][1] = pb[1][0];
;     ATT_QK(0, 0, 0);
;     bf16x8 kpre[NPRE > 0 ? NPRE : 1];
; #pragma unroll
;     for (int i_ = 0; i_ < NPRE; ++i_) kpre[i_] = *(LAS const bf16x8*)(lds + koff + i_ * 32);
	v_mfma_f32_32x32x16_bf16 v[80:95], v[80:83], v[122:125], 0
	v_add_f32_e32 v66, v65, v66
	v_cvt_pk_bf16_f32 v167, v64, v65
	v_mfma_f32_32x32x16_bf16 v[80:95], v[182:185], v[126:129], v[80:95]
	v_exp_f32_e32 v64, v68
	v_exp_f32_e32 v65, v69
	v_add_f32_e32 v66, v64, v66
	v_add_f32_e32 v66, v65, v66
	v_cvt_pk_bf16_f32 v168, v64, v65
	v_mfma_f32_32x32x16_bf16 v[80:95], v[178:181], v[130:133], v[80:95]
	v_exp_f32_e32 v64, v70
	v_exp_f32_e32 v65, v71
	v_add_f32_e32 v66, v64, v66
	v_add_f32_e32 v178, v65, v66
	v_cvt_pk_bf16_f32 v169, v64, v65
	s_waitcnt lgkmcnt(0)
	v_mfma_f32_32x32x16_bf16 v[80:95], v[170:173], v[134:137], v[80:95]
	ds_read_b128 v[64:67], v211 offset:13312
	ds_read_b128 v[68:71], v211 offset:13344
	ds_read_b128 v[182:185], v211 offset:17920
	ds_read_b128 v[248:251], v211 offset:17952
	v_exp_f32_e32 v72, v72
	v_exp_f32_e32 v73, v73
	v_add_f32_e32 v170, v72, v178
	v_add_f32_e32 v170, v73, v170
	v_cvt_pk_bf16_f32 v178, v72, v73
	v_mfma_f32_32x32x16_bf16 v[80:95], v[218:221], v[154:157], v[80:95]
	v_exp_f32_e32 v72, v74
	v_exp_f32_e32 v73, v75
	v_add_f32_e32 v74, v72, v170
	v_add_f32_e32 v74, v73, v74
	v_cvt_pk_bf16_f32 v179, v72, v73
	v_mfma_f32_32x32x16_bf16 v[80:95], v[222:225], v[158:161], v[80:95]
	v_exp_f32_e32 v72, v76
	v_exp_f32_e32 v73, v77
	v_add_f32_e32 v74, v72, v74
	v_add_f32_e32 v74, v73, v74
	v_cvt_pk_bf16_f32 v180, v72, v73
	s_waitcnt lgkmcnt(0)
	v_mfma_f32_32x32x16_bf16 v[16:31], v[64:67], v[162:165], v[16:31]
	v_exp_f32_e32 v64, v78
	v_exp_f32_e32 v65, v79
	v_add_f32_e32 v66, v64, v74
	v_add_f32_e32 v210, v65, v66
	v_cvt_pk_bf16_f32 v181, v64, v65
	v_mfma_f32_32x32x16_bf16 v[0:15], v[182:185], v[162:165], v[0:15]
	v_add_u32_e32 v226, s78, v242
	ds_read_b128 v[64:67], v226 offset:22528
	ds_read_b128 v[170:173], v226 offset:22560
	ds_read_b128 v[182:185], v226 offset:22592
	v_cmp_nge_f32_e64 s[10:11], s48, v210
	v_mfma_f32_32x32x16_bf16 v[16:31], v[68:71], v[174:177], v[16:31]
	v_exp_f32_e32 v68, v80
	v_exp_f32_e32 v69, v81
	s_nop 0
	v_add_f32_e32 v70, v69, v68
	v_cvt_pk_bf16_f32 v162, v68, v69
	v_exp_f32_e32 v80, v82
	v_exp_f32_e32 v81, v83
	v_add_f32_e32 v82, v80, v70
	v_mfma_f32_32x32x16_bf16 v[0:15], v[248:251], v[174:177], v[0:15]
	ds_read_b128 v[174:177], v226 offset:22624
	ds_read_b128 v[218:221], v226 offset:22656
	ds_read_b128 v[222:225], v226 offset:22688
	s_waitcnt lgkmcnt(3)
	v_mfma_f32_32x32x16_bf16 v[64:79], v[64:67], v[98:101], 0
	v_add_f32_e32 v82, v81, v82
	v_cvt_pk_bf16_f32 v163, v80, v81
	v_mfma_f32_32x32x16_bf16 v[64:79], v[170:173], v[102:105], v[64:79]
	v_exp_f32_e32 v80, v84
	v_exp_f32_e32 v81, v85
	v_add_f32_e32 v82, v80, v82
	v_add_f32_e32 v82, v81, v82
	v_cvt_pk_bf16_f32 v164, v80, v81
	v_mfma_f32_32x32x16_bf16 v[64:79], v[182:185], v[106:109], v[64:79]
	v_exp_f32_e32 v80, v86
	v_exp_f32_e32 v81, v87
	v_add_f32_e32 v82, v80, v82
	v_add_f32_e32 v170, v81, v82
	v_cvt_pk_bf16_f32 v165, v80, v81
	s_waitcnt lgkmcnt(0)
	v_mfma_f32_32x32x16_bf16 v[64:79], v[174:177], v[110:113], v[64:79]
	ds_read_b128 v[80:83], v211 offset:13376
	ds_read_b128 v[84:87], v211 offset:13408
	ds_read_b128 v[182:185], v211 offset:17984
	ds_read_b128 v[248:251], v211 offset:18016
	v_exp_f32_e32 v88, v88
	v_exp_f32_e32 v89, v89
	v_add_f32_e32 v170, v88, v170
	v_add_f32_e32 v171, v89, v170
	v_cvt_pk_bf16_f32 v170, v88, v89
	v_mfma_f32_32x32x16_bf16 v[64:79], v[218:221], v[114:117], v[64:79]
	v_exp_f32_e32 v88, v90
	v_exp_f32_e32 v89, v91
	v_add_f32_e32 v90, v88, v171
	v_add_f32_e32 v90, v89, v90
	v_cvt_pk_bf16_f32 v171, v88, v89
	v_mfma_f32_32x32x16_bf16 v[64:79], v[222:225], v[118:121], v[64:79]
	v_exp_f32_e32 v88, v92
	v_exp_f32_e32 v89, v93
	v_add_f32_e32 v90, v88, v90
	v_add_f32_e32 v90, v89, v90
	v_cvt_pk_bf16_f32 v172, v88, v89
	s_waitcnt lgkmcnt(0)
	v_mfma_f32_32x32x16_bf16 v[48:63], v[80:83], v[166:169], v[48:63]
	v_exp_f32_e32 v80, v94
	v_exp_f32_e32 v81, v95
	v_add_f32_e32 v82, v80, v90
	v_add_f32_e32 v211, v81, v82
	v_cvt_pk_bf16_f32 v173, v80, v81
	v_mfma_f32_32x32x16_bf16 v[32:47], v[182:185], v[166:169], v[32:47]
	ds_read_b128 v[80:83], v226 offset:22528
	ds_read_b128 v[182:185], v226 offset:22560
	ds_read_b128 v[174:177], v226 offset:22592
	v_cmp_nge_f32_e64 s[12:13], s48, v211
	v_mfma_f32_32x32x16_bf16 v[48:63], v[84:87], v[178:181], v[48:63]
	s_waitcnt lgkmcnt(0)
	s_barrier
	v_mfma_f32_32x32x16_bf16 v[32:47], v[248:251], v[178:181], v[32:47]
	s_cmpk_gt_u32 s61, 0xfc
	s_cbranch_scc1 .LBB0_933
	s_add_i32 s24, s79, 0
	v_add_u32_e32 v84, s24, v238
	v_add_u32_e32 v85, s24, v245
	v_add_u32_e32 v86, s24, v198
	s_waitcnt vmcnt(1)
	ds_write_b128 v84, v[150:153]
	s_waitcnt vmcnt(0)
	ds_write_b64 v85, v[190:191] offset:128
	ds_write_b128 v86, v[138:141] offset:13312

.LBB0_935:
	s_or_b64 s[6:7], s[8:9], s[6:7]
	v_add_f32_e32 v84, v204, v246
	v_add_f32_e32 v85, v205, v247
	s_or_b64 s[6:7], s[6:7], s[10:11]
	s_or_b64 s[6:7], s[6:7], s[12:13]
	v_pk_add_f32 v[178:179], v[84:85], v[210:211]
	s_xor_b32 s10, s77, 2
	v_add_u32_e32 v222, s78, v244
	v_exp_f32_e32 v64, v64
	v_exp_f32_e32 v65, v65
	s_nop 0
	v_add_f32_e32 v84, v65, v64
	v_cvt_pk_bf16_f32 v166, v64, v65
	v_exp_f32_e32 v64, v66
	ds_read_b128 v[204:207], v199 offset:22624
	ds_read_b128 v[208:211], v199 offset:22656
	ds_read_b128 v[218:221], v199 offset:22688
	v_exp_f32_e32 v65, v67
	v_add_f32_e32 v66, v64, v84
	v_mfma_f32_32x32x16_bf16 v[80:95], v[80:83], v[122:125], 0
	v_add_f32_e32 v66, v65, v66
	v_cvt_pk_bf16_f32 v167, v64, v65
	v_mfma_f32_32x32x16_bf16 v[80:95], v[182:185], v[126:129], v[80:95]
	v_exp_f32_e32 v64, v68
	v_exp_f32_e32 v65, v69
	v_add_f32_e32 v66, v64, v66
	v_add_f32_e32 v66, v65, v66
	v_cvt_pk_bf16_f32 v168, v64, v65
	v_mfma_f32_32x32x16_bf16 v[80:95], v[174:177], v[130:133], v[80:95]
	v_exp_f32_e32 v64, v70
	v_exp_f32_e32 v65, v71
	v_add_f32_e32 v66, v64, v66
	v_add_f32_e32 v174, v65, v66
	v_cvt_pk_bf16_f32 v169, v64, v65
	s_waitcnt lgkmcnt(0)
	v_mfma_f32_32x32x16_bf16 v[80:95], v[204:207], v[134:137], v[80:95]
	ds_read_b128 v[64:67], v222 offset:13376
	ds_read_b128 v[68:71], v222 offset:13408
	ds_read_b128 v[180:183], v222 offset:17984
	ds_read_b128 v[222:225], v222 offset:18016
	v_exp_f32_e32 v72, v72
	v_exp_f32_e32 v73, v73
	v_add_f32_e32 v174, v72, v174
	v_add_f32_e32 v175, v73, v174
	v_cvt_pk_bf16_f32 v174, v72, v73
	v_mfma_f32_32x32x16_bf16 v[80:95], v[208:211], v[154:157], v[80:95]
	v_exp_f32_e32 v72, v74
	v_exp_f32_e32 v73, v75
	v_add_f32_e32 v74, v72, v175
	v_add_f32_e32 v74, v73, v74
	v_cvt_pk_bf16_f32 v175, v72, v73
	v_mfma_f32_32x32x16_bf16 v[80:95], v[218:221], v[158:161], v[80:95]
	v_exp_f32_e32 v72, v76
	v_exp_f32_e32 v73, v77
	v_add_f32_e32 v74, v72, v74
	v_add_f32_e32 v74, v73, v74
	v_cvt_pk_bf16_f32 v176, v72, v73
	s_waitcnt lgkmcnt(0)
	v_mfma_f32_32x32x16_bf16 v[16:31], v[64:67], v[162:165], v[16:31]
	v_exp_f32_e32 v64, v78
	v_exp_f32_e32 v65, v79
	v_add_f32_e32 v66, v64, v74
	v_add_f32_e32 v204, v65, v66
	v_cvt_pk_bf16_f32 v177, v64, v65
	v_mfma_f32_32x32x16_bf16 v[0:15], v[180:183], v[162:165], v[0:15]
	ds_read_b128 v[64:67], v199 offset:29184
	ds_read_b128 v[180:183], v199 offset:29216
	ds_read_b128 v[208:211], v199 offset:29248
	v_cmp_nge_f32_e32 vcc, s48, v204
	v_mfma_f32_32x32x16_bf16 v[16:31], v[68:71], v[170:173], v[16:31]
	v_mfma_f32_32x32x16_bf16 v[0:15], v[222:225], v[170:173], v[0:15]
	v_mad_u32_u24 v68, v187, s69, v186
	v_add_u32_e32 v206, s76, v68
	v_exp_f32_e32 v68, v80
	v_exp_f32_e32 v69, v81
	s_nop 0
	v_add_f32_e32 v70, v69, v68
	v_cvt_pk_bf16_f32 v162, v68, v69
	v_exp_f32_e32 v80, v82
	ds_read_b128 v[170:173], v199 offset:29280
	ds_read_b128 v[218:221], v199 offset:29312
	ds_read_b128 v[222:225], v199 offset:29344
	v_exp_f32_e32 v81, v83
	v_add_f32_e32 v82, v80, v70
	s_waitcnt lgkmcnt(3)
	v_mfma_f32_32x32x16_bf16 v[64:79], v[64:67], v[98:101], 0
	v_add_f32_e32 v82, v81, v82
	v_cvt_pk_bf16_f32 v163, v80, v81
	v_mfma_f32_32x32x16_bf16 v[64:79], v[180:183], v[102:105], v[64:79]
	v_exp_f32_e32 v80, v84
	v_exp_f32_e32 v81, v85
	v_add_f32_e32 v82, v80, v82
	v_add_f32_e32 v82, v81, v82
	v_cvt_pk_bf16_f32 v164, v80, v81
	v_mfma_f32_32x32x16_bf16 v[64:79], v[208:211], v[106:109], v[64:79]
	v_exp_f32_e32 v80, v86
	v_exp_f32_e32 v81, v87
	v_add_f32_e32 v82, v80, v82
	v_add_f32_e32 v184, v81, v82
	v_cvt_pk_bf16_f32 v165, v80, v81
	s_waitcnt lgkmcnt(0)
	v_mfma_f32_32x32x16_bf16 v[64:79], v[170:173], v[110:113], v[64:79]
	ds_read_b128 v[80:83], v206 offset:35840
	ds_read_b128 v[84:87], v206 offset:35872
	ds_read_b128 v[180:183], v206 offset:40448
	ds_read_b128 v[208:211], v206 offset:40480
	v_exp_f32_e32 v88, v88
	v_exp_f32_e32 v89, v89
	v_add_f32_e32 v170, v88, v184
	v_add_f32_e32 v171, v89, v170
	v_cvt_pk_bf16_f32 v170, v88, v89
	v_mfma_f32_32x32x16_bf16 v[64:79], v[218:221], v[114:117], v[64:79]
	v_exp_f32_e32 v88, v90
	v_exp_f32_e32 v89, v91
	v_add_f32_e32 v90, v88, v171
	v_add_f32_e32 v90, v89, v90
	v_cvt_pk_bf16_f32 v171, v88, v89
	v_mfma_f32_32x32x16_bf16 v[64:79], v[222:225], v[118:121], v[64:79]
	v_exp_f32_e32 v88, v92
	v_exp_f32_e32 v89, v93
	v_add_f32_e32 v90, v88, v90
	v_add_f32_e32 v90, v89, v90
	v_cvt_pk_bf16_f32 v172, v88, v89
	s_waitcnt lgkmcnt(0)
	v_mfma_f32_32x32x16_bf16 v[48:63], v[80:83], v[166:169], v[48:63]
	v_exp_f32_e32 v80, v94
	v_exp_f32_e32 v81, v95
	v_add_f32_e32 v82, v80, v90
	v_add_f32_e32 v205, v81, v82
	v_cvt_pk_bf16_f32 v173, v80, v81
	v_mfma_f32_32x32x16_bf16 v[32:47], v[180:183], v[166:169], v[32:47]
	ds_read_b128 v[80:83], v199 offset:29184
	ds_read_b128 v[166:169], v199 offset:29216
	ds_read_b128 v[182:185], v199 offset:29248
	s_or_b64 s[8:9], s[6:7], vcc
	v_cmp_nge_f32_e32 vcc, s48, v205
	v_pk_add_f32 v[204:205], v[178:179], v[204:205]
	v_mfma_f32_32x32x16_bf16 v[48:63], v[84:87], v[174:177], v[48:63]
	v_exp_f32_e32 v64, v64
	v_exp_f32_e32 v65, v65
	s_nop 0
	v_add_f32_e32 v84, v65, v64
	v_cvt_pk_bf16_f32 v178, v64, v65
	v_exp_f32_e32 v64, v66
	v_exp_f32_e32 v65, v67
	v_add_f32_e32 v66, v64, v84
	v_mfma_f32_32x32x16_bf16 v[32:47], v[208:211], v[174:177], v[32:47]
	ds_read_b128 v[174:177], v199 offset:29280
	ds_read_b128 v[208:211], v199 offset:29312
	ds_read_b128 v[218:221], v199 offset:29344
	s_waitcnt lgkmcnt(3)
; #define LAS __attribute__((address_space(3)))
; template <int MODE, bool FAST> __device__ __forceinline__ bool attn_unit(LAS unsigned char* lds, const AttU& U, const int wv) {
;     ...
;     pb[1][0] = (bf16x8){0, 0, 0, 0, 0, 0, 0, 0}; pb[1][1] = pb[1][0];
;     ATT_QK(0, 0, 0);
;     bf16x8 kpre[NPRE > 0 ? NPRE : 1];
; #pragma unroll
;     for (int i_ = 0; i_ < NPRE; ++i_) kpre[i_] = *(LAS const bf16x8*)(lds + koff + i_ * 32);
;     ...
;     if constexpr (FAST) {
;         for (int t2 = U.kt0; t2 < U.kt1; t2 += 2) { ATT_TILE(t2, 4, rk, rr, rv); ATT_TILE(t2 + 1, 4, rk2, rr2, rv2); }
	v_mfma_f32_32x32x16_bf16 v[80:95], v[80:83], v[122:125], 0
	v_add_f32_e32 v66, v65, v66
	v_cvt_pk_bf16_f32 v179, v64, v65
	v_mfma_f32_32x32x16_bf16 v[80:95], v[166:169], v[126:129], v[80:95]
	v_exp_f32_e32 v64, v68
	v_exp_f32_e32 v65, v69
	v_add_f32_e32 v66, v64, v66
	v_add_f32_e32 v66, v65, v66
	v_cvt_pk_bf16_f32 v180, v64, v65
	v_mfma_f32_32x32x16_bf16 v[80:95], v[182:185], v[130:133], v[80:95]
	v_exp_f32_e32 v64, v70
	v_exp_f32_e32 v65, v71
	v_add_f32_e32 v66, v64, v66
	v_add_f32_e32 v182, v65, v66
	v_cvt_pk_bf16_f32 v181, v64, v65
	s_waitcnt lgkmcnt(0)
	v_mfma_f32_32x32x16_bf16 v[80:95], v[174:177], v[134:137], v[80:95]
	ds_read_b128 v[64:67], v206 offset:35840
	ds_read_b128 v[68:71], v206 offset:35872
	ds_read_b128 v[166:169], v206 offset:40448
	ds_read_b128 v[222:225], v206 offset:40480
	v_exp_f32_e32 v72, v72
	v_exp_f32_e32 v73, v73
	v_add_f32_e32 v174, v72, v182
	v_add_f32_e32 v174, v73, v174
	v_cvt_pk_bf16_f32 v182, v72, v73
	v_mfma_f32_32x32x16_bf16 v[80:95], v[208:211], v[154:157], v[80:95]
	v_exp_f32_e32 v72, v74
	v_exp_f32_e32 v73, v75
	v_add_f32_e32 v74, v72, v174
	v_add_f32_e32 v74, v73, v74
	v_cvt_pk_bf16_f32 v183, v72, v73
	v_mfma_f32_32x32x16_bf16 v[80:95], v[218:221], v[158:161], v[80:95]
	v_exp_f32_e32 v72, v76
	v_exp_f32_e32 v73, v77
	v_add_f32_e32 v74, v72, v74
	v_add_f32_e32 v74, v73, v74
	v_cvt_pk_bf16_f32 v184, v72, v73
	s_waitcnt lgkmcnt(0)
	v_mfma_f32_32x32x16_bf16 v[16:31], v[64:67], v[162:165], v[16:31]
	v_exp_f32_e32 v64, v78
	v_exp_f32_e32 v65, v79
	v_add_f32_e32 v66, v64, v74
	v_add_f32_e32 v226, v65, v66
	v_cvt_pk_bf16_f32 v185, v64, v65
	v_mfma_f32_32x32x16_bf16 v[0:15], v[166:169], v[162:165], v[0:15]
	s_mulk_i32 s10, 0x5800
	v_add_u32_e32 v199, s10, v242
	ds_read_b128 v[64:67], v199
	ds_read_b128 v[164:167], v199 offset:32
	ds_read_b128 v[174:177], v199 offset:64
	v_cmp_nge_f32_e64 s[6:7], s48, v226
	v_mfma_f32_32x32x16_bf16 v[16:31], v[68:71], v[170:173], v[16:31]
	v_exp_f32_e32 v68, v80
	v_exp_f32_e32 v69, v81
	s_nop 0
	v_add_f32_e32 v70, v69, v68
	v_cvt_pk_bf16_f32 v162, v68, v69
	v_exp_f32_e32 v80, v82
	v_exp_f32_e32 v81, v83
	v_add_f32_e32 v82, v80, v70
	v_mfma_f32_32x32x16_bf16 v[0:15], v[222:225], v[170:173], v[0:15]
	s_or_b64 s[8:9], s[8:9], vcc
	ds_read_b128 v[168:171], v199 offset:96
	ds_read_b128 v[208:211], v199 offset:128
	ds_read_b128 v[218:221], v199 offset:160
	s_waitcnt lgkmcnt(3)
	v_mfma_f32_32x32x16_bf16 v[64:79], v[64:67], v[98:101], 0
	v_add_f32_e32 v82, v81, v82
	v_cvt_pk_bf16_f32 v163, v80, v81
	v_mfma_f32_32x32x16_bf16 v[64:79], v[164:167], v[102:105], v[64:79]
	v_exp_f32_e32 v80, v84
	v_exp_f32_e32 v81, v85
	v_add_f32_e32 v82, v80, v82
	v_add_f32_e32 v82, v81, v82
	v_cvt_pk_bf16_f32 v164, v80, v81
	v_mfma_f32_32x32x16_bf16 v[64:79], v[174:177], v[106:109], v[64:79]
	v_exp_f32_e32 v80, v86
	v_exp_f32_e32 v81, v87
	v_add_f32_e32 v82, v80, v82
	v_add_f32_e32 v166, v81, v82
	v_cvt_pk_bf16_f32 v165, v80, v81
	s_waitcnt lgkmcnt(0)
	v_mfma_f32_32x32x16_bf16 v[64:79], v[168:171], v[110:113], v[64:79]
	ds_read_b128 v[80:83], v206 offset:35904
	ds_read_b128 v[84:87], v206 offset:35936
	ds_read_b128 v[222:225], v206 offset:40512
	ds_read_b128 v[246:249], v206 offset:40544
	v_exp_f32_e32 v88, v88
	v_exp_f32_e32 v89, v89
	v_add_f32_e32 v166, v88, v166
	v_add_f32_e32 v167, v89, v166
	v_cvt_pk_bf16_f32 v166, v88, v89
	v_mfma_f32_32x32x16_bf16 v[64:79], v[208:211], v[114:117], v[64:79]
	v_exp_f32_e32 v88, v90
	v_exp_f32_e32 v89, v91
	v_add_f32_e32 v90, v88, v167
	v_add_f32_e32 v90, v89, v90
	v_cvt_pk_bf16_f32 v167, v88, v89
	v_mfma_f32_32x32x16_bf16 v[64:79], v[218:221], v[118:121], v[64:79]
	v_exp_f32_e32 v88, v92
	v_exp_f32_e32 v89, v93
	v_add_f32_e32 v90, v88, v90
	v_add_f32_e32 v90, v89, v90
	v_cvt_pk_bf16_f32 v168, v88, v89
	s_waitcnt lgkmcnt(0)
	v_mfma_f32_32x32x16_bf16 v[48:63], v[80:83], v[178:181], v[48:63]
	v_exp_f32_e32 v80, v94
	v_exp_f32_e32 v81, v95
	v_add_f32_e32 v82, v80, v90
	v_add_f32_e32 v227, v81, v82
	v_cvt_pk_bf16_f32 v169, v80, v81
	v_mfma_f32_32x32x16_bf16 v[32:47], v[222:225], v[178:181], v[32:47]
	ds_read_b128 v[80:83], v199
	ds_read_b128 v[174:177], v199 offset:32
	ds_read_b128 v[170:173], v199 offset:64
	s_or_b64 s[6:7], s[8:9], s[6:7]
	v_cmp_nge_f32_e32 vcc, s48, v227
	s_or_b64 s[6:7], s[6:7], vcc
	s_cmp_lg_u64 s[6:7], 0
	s_cselect_b64 s[6:7], -1, 0
	s_or_b64 s[42:43], s[42:43], s[6:7]
	v_mfma_f32_32x32x16_bf16 v[48:63], v[84:87], v[182:185], v[48:63]
	v_add_f32_e64 v204, v204, v226
	v_add_f32_e64 v205, v205, v227
	s_waitcnt lgkmcnt(0)
	s_barrier
	v_mfma_f32_32x32x16_bf16 v[32:47], v[246:249], v[182:185], v[32:47]
	s_add_u32 s40, s40, 0x40000
	s_mov_b64 s[6:7], 0x2000
	s_addc_u32 s41, s41, 0
	v_lshl_add_u64 v[202:203], v[202:203], 0, s[6:7]
	s_and_b64 vcc, exec, s[44:45]
	s_cbranch_vccnz .LBB0_937
	s_mov_b32 s61, s30
	s_branch .LBB0_923
